# scan chunk bookkeeping incremental, output-pointer increments placed after the chunk barrier (not right behind the store that reads them)
# baseline (speedup 1.0000x reference)
; #define LAS __attribute__((address_space(3)))
; __device__ __forceinline__ float bflo(unsigned w) { return __uint_as_float(w << 16); }
; __device__ __forceinline__ float bfhi(unsigned w) { return __uint_as_float(w & 0xffff0000u); }
; __device__ __forceinline__ void scan_load_chunk(LAS unsigned char* slot, const float* Wd, const float* V, const bf16_t* RKKB, int p, int rg, int s0, int lt) {
;     ...
;     for (int j = 0; j < 2; ++j) { const int idx = lt + 256 * j, st = idx >> 4, part = idx & 15; *(LAS u32x4*)(slot + st * SCAN_STEP_B + part * 16) = r[j]; }
; #pragma unroll
;     for (int j = 2; j < 6; ++j) { const int k = lt + 256 * (j - 2), st = k >> 5, rem = k & 31, q = rem >> 3, part = rem & 7; const u32x4 w = r[j];
;         const int Q = (q == 0) ? 4 : (q == 1) ? 2 : (q == 2) ? 3 : 1;
;         LAS f32x4* d = (LAS f32x4*)(slot + st * SCAN_STEP_B + Q * 256 + part * 32);
;         d[0] = (f32x4){bflo(w.x), bfhi(w.x), bflo(w.y), bfhi(w.y)}; d[1] = (f32x4){bflo(w.z), bfhi(w.z), bflo(w.w), bfhi(w.w)}; }
;     if (lt < 128) { const int st = lt >> 2, hf = lt & 3; *(LAS u32x4*)(slot + st * SCAN_STEP_B + 1280 + hf * 16) = r[6]; }
; }
; __device__ __forceinline__ void rwkv_scan_unit(LAS unsigned char* lds, const float* Wd, const float* V, const bf16_t* RKKB, float* Yraw, int p, int rg, int tid) {
;     const int lane = tid & 63, wave = __builtin_amdgcn_readfirstlane(tid >> 6);
;     constexpr int NCH = SEQ / SCAN_CH;
;     scan_load_chunk(lds + (tid >> 8) * SCAN_SLOT_B, Wd, V, RKKB, p, rg, (tid >> 8) * SCAN_CH, tid & 255);
;     __syncthreads();
;     f32x4 S = (f32x4){0.f, 0.f, 0.f, 0.f};
;     const int kq = lane & 15, rl = wave * 4 + (lane >> 4);
;     for (int c = 0; c < NCH; ++c) {
;         if (wave >= 4) { if (c + 2 < NCH) scan_load_chunk(lds + ((c + 2) % 3) * SCAN_SLOT_B, Wd, V, RKKB, p, rg, (c + 2) * SCAN_CH, tid - 256); }
;         else {
;             LAS const unsigned char* sl = lds + (c % 3) * SCAN_SLOT_B + kq * 16;
;             LAS const unsigned char* vl = lds + (c % 3) * SCAN_SLOT_B + 1280 + rl * 4;
;             float* yo = Yraw + ((size_t)p * SEQ + c * SCAN_CH + kq) * 64 + rg * 16 + rl;
;             f32x4 w = *(LAS const f32x4*)(sl), b = *(LAS const f32x4*)(sl + 256), k = *(LAS const f32x4*)(sl + 512), kk = *(LAS const f32x4*)(sl + 768), r = *(LAS const f32x4*)(sl + 1024);
;             float v = *(LAS const float*)(vl); float yp[16];
.LBB0_340:
	s_or_b64 exec, exec, s[6:7]
	v_add3_u32 v14, v14, v10, v22
	s_waitcnt vmcnt(0)
	v_lshlrev_b32_e32 v10, 16, v2
	v_and_b32_e32 v11, 0xffff0000, v2
	v_lshlrev_b32_e32 v12, 16, v3
	v_and_b32_e32 v13, 0xffff0000, v3
	v_lshlrev_b32_e32 v2, 16, v4
	v_and_b32_e32 v3, 0xffff0000, v4
	v_lshlrev_b32_e32 v4, 16, v5
	v_and_b32_e32 v5, 0xffff0000, v5
	ds_write_b128 v14, v[10:13] offset:10752
	ds_write_b128 v14, v[2:5] offset:10768
	s_and_saveexec_b64 s[6:7], s[4:5]
	v_lshrrev_b32_e32 v2, 8, v232
	v_lshlrev_b32_e32 v2, 11, v2
	v_and_b32_e32 v3, 3, v232
	v_lshl_or_b32 v2, v3, 9, v2
	v_and_b32_e32 v3, 0xfc, v232
	v_or_b32_e32 v2, v2, v3
	v_add_u32_e32 v2, 0x1f800, v2
	ds_write_b32 v2, v6
	ds_write_b32 v2, v7 offset:128
	ds_write_b32 v2, v8 offset:256
	ds_write_b32 v2, v9 offset:384
	s_or_b64 exec, exec, s[6:7]
	v_and_b32_e32 v3, 4, v32
	v_cmp_eq_u32_e64 s[6:7], 0, v3
	v_and_b32_e32 v3, 1, v32
	s_ashr_i32 s4, s10, 6
	v_and_b32_e32 v4, 2, v32
	v_cmp_eq_u32_e64 s[10:11], 0, v3
	v_add_u32_e32 v3, 0xffffff00, v32
	v_add_u32_e32 v12, 0x100, v32
	v_add_u32_e32 v14, 0x200, v32
	s_cmp_lt_i32 s4, 4
	v_cmp_eq_u32_e64 s[8:9], 0, v4
	v_ashrrev_i32_e32 v4, 4, v3
	v_ashrrev_i32_e32 v6, 4, v32
	v_ashrrev_i32_e32 v8, 5, v3
	v_ashrrev_i32_e32 v10, 5, v32
	v_ashrrev_i32_e32 v12, 5, v12
	v_ashrrev_i32_e32 v14, 5, v14
	v_ashrrev_i32_e32 v16, 2, v3
	s_movk_i32 s19, 0x540
	s_cselect_b64 s[16:17], -1, 0
	v_mul_lo_u32 v74, v4, s19
	v_mul_lo_u32 v75, v6, s19
	v_mul_lo_u32 v77, v8, s19
	v_mul_lo_u32 v78, v10, s19
	v_mul_lo_u32 v79, v12, s19
	v_mul_lo_u32 v80, v14, s19
	v_mul_lo_u32 v81, v16, s19
	s_and_b32 s23, s20, 7
	s_ashr_i32 s19, s18, 31
	s_lshl_b32 s21, s23, 22
	s_lshl_b64 s[24:25], s[18:19], 20
	v_ashrrev_i32_e32 v17, 31, v16
	v_lshlrev_b32_e32 v19, 5, v32
	s_add_u32 s24, s21, s24
	v_and_b32_e32 v76, 0xe0, v19
	s_addc_u32 s25, 0, s25
	v_lshlrev_b64 v[16:17], 8, v[16:17]
	s_lshl_b32 s20, s20, 3
	v_and_b32_e32 v19, 3, v3
	v_lshl_add_u64 v[16:17], s[24:25], 0, v[16:17]
	s_and_b32 s26, s20, 0xc0
	v_lshlrev_b32_e32 v19, 4, v19
	v_readlane_b32 s20, v254, 47
	v_or3_b32 v16, v16, s26, v19
	v_readlane_b32 s21, v254, 48
	s_lshl_b32 s27, s23, 23
	v_ashrrev_i32_e32 v5, 31, v4
	v_lshl_add_u64 v[46:47], s[20:21], 0, v[16:17]
	s_lshl_b64 s[20:21], s[18:19], 21
	v_ashrrev_i32_e32 v7, 31, v6
	v_ashrrev_i32_e32 v9, 31, v8
	v_ashrrev_i32_e32 v11, 31, v10
	v_ashrrev_i32_e32 v13, 31, v12
	v_ashrrev_i32_e32 v15, 31, v14
	s_add_u32 s20, s27, s20
	v_lshlrev_b32_e32 v18, 4, v3
	s_addc_u32 s21, 0, s21
	v_lshlrev_b64 v[14:15], 9, v[14:15]
	v_lshlrev_b64 v[12:13], 9, v[12:13]
	v_lshlrev_b64 v[10:11], 9, v[10:11]
	v_lshlrev_b64 v[8:9], 9, v[8:9]
	v_lshlrev_b64 v[6:7], 8, v[6:7]
	v_lshlrev_b64 v[4:5], 8, v[4:5]
	v_and_b32_e32 v73, 0xf0, v18
	v_lshl_add_u64 v[14:15], s[20:21], 0, v[14:15]
	v_lshl_add_u64 v[12:13], s[20:21], 0, v[12:13]
	v_lshl_add_u64 v[10:11], s[20:21], 0, v[10:11]
	v_lshl_add_u64 v[8:9], s[20:21], 0, v[8:9]
	v_lshl_add_u64 v[6:7], s[24:25], 0, v[6:7]
	v_readlane_b32 s20, v254, 51
	v_lshl_add_u64 v[4:5], s[24:25], 0, v[4:5]
	v_or_b32_e32 v6, v6, v73
	v_readlane_b32 s21, v254, 52
	v_or_b32_e32 v4, v4, v73
	s_lshl_b64 s[18:19], s[18:19], 12
	v_lshl_add_u64 v[56:57], s[20:21], 0, v[6:7]
	v_lshl_add_u64 v[58:59], s[20:21], 0, v[4:5]
	s_lshl_b32 s20, s23, 14
	s_add_u32 s18, s20, s18
	v_and_b32_e32 v0, 15, v32
	s_addc_u32 s19, 0, s19
	v_bfe_u32 v2, v32, 4, 2
	v_and_b32_e32 v3, 7, v3
	v_or_b32_e32 v4, s18, v0
	v_mov_b32_e32 v5, s19
	v_lshl_or_b32 v2, s4, 2, v2
	v_and_b32_e32 v16, 0x180, v18
	v_lshlrev_b32_e32 v3, 4, v3
	v_lshlrev_b64 v[4:5], 8, v[4:5]
	v_or3_b32 v14, v14, v16, v3
	v_or3_b32 v12, v12, v16, v3
	v_or3_b32 v10, v10, v16, v3
	v_or3_b32 v8, v8, v16, v3
	v_or_b32_e32 v4, s26, v4
	v_ashrrev_i32_e32 v3, 31, v2
	v_lshlrev_b32_e32 v72, 2, v2
	v_lshl_add_u64 v[2:3], v[2:3], 2, v[4:5]
	v_readlane_b32 s28, v254, 49
	v_lshl_add_u64 v[60:61], s[92:93], 0, v[2:3]
	v_mov_b32_e32 v2, v1
	v_mov_b32_e32 v3, v1
	v_lshlrev_b32_e32 v71, 4, v0
	v_cmp_gt_u32_e64 s[4:5], 8, v0
	s_movk_i32 s12, 0x180
	v_readlane_b32 s29, v254, 50
	v_mov_b32_e32 v0, v1
	v_mov_b64_e32 v[4:5], v[2:3]
	s_mov_b32 s22, 0
	v_cmp_gt_i32_e64 s[12:13], s12, v32
	v_and_b32_e32 v82, 48, v18
	v_lshl_add_u64 v[48:49], s[28:29], 0, v[14:15]
	v_lshl_add_u64 v[50:51], s[28:29], 0, v[12:13]
	v_lshl_add_u64 v[52:53], s[28:29], 0, v[10:11]
	v_lshl_add_u64 v[54:55], s[28:29], 0, v[8:9]
	v_mov_b64_e32 v[2:3], v[0:1]
	s_waitcnt lgkmcnt(0)
	s_barrier
	s_and_b64 vcc, exec, s[16:17]
	s_cbranch_vccz .Lscan_ldprime
	s_setprio 3
	v_lshlrev_b32_e32 v96, 5, v72
	v_add_u32_e32 v96, 0x1f800, v96
	ds_read_b128 v[116:119], v96
	ds_read_b128 v[132:135], v71 offset:768
	ds_read_b128 v[120:123], v71
	ds_read_b128 v[128:131], v71 offset:512
	ds_read_b128 v[124:127], v71 offset:256
	ds_read_b128 v[136:139], v71 offset:1024
	ds_read_b128 v[156:159], v71 offset:2112
	ds_read_b128 v[144:147], v71 offset:1344
	ds_read_b128 v[152:155], v71 offset:1856
	ds_read_b128 v[148:151], v71 offset:1600
	ds_read_b128 v[160:163], v71 offset:2368
	s_mov_b32 s18, 0
	s_mov_b32 s19, 0xa800
	v_lshl_add_u64 v[62:63], v[60:61], 0, s[14:15]
	s_mov_b64 s[20:21], 0x160fe000
	v_lshl_add_u64 v[88:89], v[62:63], 0, s[20:21]
	s_mov_b64 s[20:21], 0x160ff000
	v_lshl_add_u64 v[90:91], v[62:63], 0, s[20:21]
	s_branch .Lscan_top

; #define LAS __attribute__((address_space(3)))
; __device__ __forceinline__ float row16_sum(float v) { v += dpp_f<0xB1>(v); v += dpp_f<0x4E>(v); v += dpp_f<0x141>(v); v += dpp_f<0x140>(v); return v; }
; __device__ __forceinline__ void rwkv_scan_unit(LAS unsigned char* lds, const float* Wd, const float* V, const bf16_t* RKKB, float* Yraw, int p, int rg, int tid) {
;     ...
;     for (int c = 0; c < NCH; ++c) {
;         if (wave >= 4) { if (c + 2 < NCH) scan_load_chunk(lds + ((c + 2) % 3) * SCAN_SLOT_B, Wd, V, RKKB, p, rg, (c + 2) * SCAN_CH, tid - 256); }
;         else {
;             LAS const unsigned char* sl = lds + (c % 3) * SCAN_SLOT_B + kq * 16;
;             LAS const unsigned char* vl = lds + (c % 3) * SCAN_SLOT_B + 1280 + rl * 4;
;             float* yo = Yraw + ((size_t)p * SEQ + c * SCAN_CH + kq) * 64 + rg * 16 + rl;
;             f32x4 w = *(LAS const f32x4*)(sl), b = *(LAS const f32x4*)(sl + 256), k = *(LAS const f32x4*)(sl + 512), kk = *(LAS const f32x4*)(sl + 768), r = *(LAS const f32x4*)(sl + 1024);
;             float v = *(LAS const float*)(vl); float yp[16];
; #pragma unroll
;             for (int st = 0; st < SCAN_CH; ++st) {
;                 f32x4 wn = w, bn = b, kn = k, kkn = kk, rn = r; float vn = v;
;                 if (st + 1 < SCAN_CH) { const int o = (st + 1) * SCAN_STEP_B;
;                     wn = *(LAS const f32x4*)(sl + o); bn = *(LAS const f32x4*)(sl + o + 256); kn = *(LAS const f32x4*)(sl + o + 512); kkn = *(LAS const f32x4*)(sl + o + 768); rn = *(LAS const f32x4*)(sl + o + 1024);
;                     vn = *(LAS const float*)(vl + o); }
;                 float sa = (S[0] * kk[0] + S[1] * kk[1]) + (S[2] * kk[2] + S[3] * kk[3]);
;                 const f32x4 kvt = k * v;
;                 sa = -row16_sum(sa);
;                 S = S * w + (b * sa + kvt);
;                 yp[st & 15] = (S[0] * r[0] + S[1] * r[1]) + (S[2] * r[2] + S[3] * r[3]);
;                 if ((st & 15) == 15) yo[(size_t)(st - 15) * 64] = tr16_sum(yp, kq);
;                 w = wn; b = bn; k = kn; kk = kkn; r = rn; v = vn;
.Lscan_top:
	s_mov_b64 s[68:69], 0x2000
	v_lshl_add_u64 v[88:89], v[88:89], 0, s[68:69]
	v_lshl_add_u64 v[90:91], v[90:91], 0, s[68:69]
	v_add_u32_e32 v84, s18, v71
	v_add_u32_e32 v86, s19, v71
	s_lshr_b32 s20, s18, 15
	s_lshl_b32 s20, s20, 11
	s_add_i32 s20, s20, 0x1f800
	v_lshl_add_u32 v96, v72, 5, s20
	s_lshr_b32 s21, s19, 15
	s_lshl_b32 s21, s21, 11
	s_add_i32 s21, s21, 0x1f800
	v_lshl_add_u32 v97, v72, 5, s21
	s_waitcnt lgkmcnt(5)
	v_pk_mul_f32 v[10:11], v[2:3], v[132:133]
	v_pk_fma_f32 v[10:11], v[4:5], v[134:135], v[10:11]
	v_pk_mul_f32 v[6:7], v[128:129], v[116:117] op_sel_hi:[1,0]
	v_add_f32_e32 v12, v10, v11
	v_pk_mul_f32 v[8:9], v[130:131], v[116:117] op_sel_hi:[1,0]
	v_pk_fma_f32 v[6:7], v[2:3], v[120:121], v[6:7]
	v_add_f32_dpp v12, v12, v12 quad_perm:[1,0,3,2] row_mask:0xf bank_mask:0xf bound_ctrl:1
	v_pk_fma_f32 v[8:9], v[4:5], v[122:123], v[8:9]
	ds_read_b128 v[180:183], v84 offset:3456
	v_add_f32_dpp v12, v12, v12 quad_perm:[2,3,0,1] row_mask:0xf bank_mask:0xf bound_ctrl:1
	ds_read_b128 v[168:171], v84 offset:2688
	ds_read_b128 v[176:179], v84 offset:3200
	v_add_f32_dpp v12, v12, v12 row_half_mirror row_mask:0xf bank_mask:0xf bound_ctrl:1
	ds_read_b128 v[172:175], v84 offset:2944
	ds_read_b128 v[184:187], v84 offset:3712
	v_add_f32_dpp v12, v12, v12 row_mirror row_mask:0xf bank_mask:0xf bound_ctrl:1
	v_pk_fma_f32 v[2:3], v[124:125], v[12:13], v[6:7] op_sel_hi:[1,0,1] neg_lo:[0,1,0] neg_hi:[0,1,0]
	v_pk_fma_f32 v[4:5], v[126:127], v[12:13], v[8:9] op_sel_hi:[1,0,1] neg_lo:[0,1,0] neg_hi:[0,1,0]
	s_waitcnt lgkmcnt(5)
	v_pk_mul_f32 v[10:11], v[2:3], v[156:157]
	v_pk_fma_f32 v[10:11], v[4:5], v[158:159], v[10:11]
	v_pk_mul_f32 v[14:15], v[2:3], v[136:137]
	v_add_f32_e32 v12, v10, v11
	v_pk_fma_f32 v[14:15], v[4:5], v[138:139], v[14:15]
	v_add_f32_e32 v100, v14, v15
	v_add_f32_dpp v12, v12, v12 quad_perm:[1,0,3,2] row_mask:0xf bank_mask:0xf bound_ctrl:1
	v_pk_mul_f32 v[6:7], v[152:153], v[116:117] op_sel:[0,1] op_sel_hi:[1,1]
	v_pk_mul_f32 v[8:9], v[154:155], v[116:117] op_sel:[0,1] op_sel_hi:[1,1]
	v_add_f32_dpp v12, v12, v12 quad_perm:[2,3,0,1] row_mask:0xf bank_mask:0xf bound_ctrl:1
	v_pk_fma_f32 v[6:7], v[2:3], v[144:145], v[6:7]
	v_pk_fma_f32 v[8:9], v[4:5], v[146:147], v[8:9]
	v_add_f32_dpp v12, v12, v12 row_half_mirror row_mask:0xf bank_mask:0xf bound_ctrl:1
	ds_read_b128 v[34:37], v84 offset:4800
	ds_read_b128 v[22:25], v84 offset:4032
	v_add_f32_dpp v12, v12, v12 row_mirror row_mask:0xf bank_mask:0xf bound_ctrl:1
	ds_read_b128 v[30:33], v84 offset:4544
	ds_read_b128 v[26:29], v84 offset:4288
	ds_read_b128 v[38:41], v84 offset:5056
	v_pk_fma_f32 v[2:3], v[148:149], v[12:13], v[6:7] op_sel_hi:[1,0,1] neg_lo:[0,1,0] neg_hi:[0,1,0]
	v_pk_fma_f32 v[4:5], v[150:151], v[12:13], v[8:9] op_sel_hi:[1,0,1] neg_lo:[0,1,0] neg_hi:[0,1,0]
	s_waitcnt lgkmcnt(5)
	v_pk_mul_f32 v[10:11], v[2:3], v[180:181]
	v_pk_fma_f32 v[10:11], v[4:5], v[182:183], v[10:11]
	v_pk_mul_f32 v[14:15], v[2:3], v[160:161]
	v_add_f32_e32 v12, v10, v11
	v_pk_fma_f32 v[14:15], v[4:5], v[162:163], v[14:15]
	v_add_f32_e32 v101, v14, v15
	v_add_f32_dpp v12, v12, v12 quad_perm:[1,0,3,2] row_mask:0xf bank_mask:0xf bound_ctrl:1
	v_pk_mul_f32 v[6:7], v[176:177], v[118:119] op_sel_hi:[1,0]
	v_pk_mul_f32 v[8:9], v[178:179], v[118:119] op_sel_hi:[1,0]
	v_add_f32_dpp v12, v12, v12 quad_perm:[2,3,0,1] row_mask:0xf bank_mask:0xf bound_ctrl:1
	v_pk_fma_f32 v[6:7], v[2:3], v[168:169], v[6:7]
	v_pk_fma_f32 v[8:9], v[4:5], v[170:171], v[8:9]
	v_add_f32_dpp v12, v12, v12 row_half_mirror row_mask:0xf bank_mask:0xf bound_ctrl:1
	ds_read_b128 v[132:135], v84 offset:6144
	ds_read_b128 v[120:123], v84 offset:5376
	v_add_f32_dpp v12, v12, v12 row_mirror row_mask:0xf bank_mask:0xf bound_ctrl:1
	ds_read_b128 v[128:131], v84 offset:5888
	ds_read_b128 v[92:95], v96 offset:16
	ds_read_b128 v[124:127], v84 offset:5632
	ds_read_b128 v[136:139], v84 offset:6400
	v_pk_fma_f32 v[2:3], v[172:173], v[12:13], v[6:7] op_sel_hi:[1,0,1] neg_lo:[0,1,0] neg_hi:[0,1,0]
	v_pk_fma_f32 v[4:5], v[174:175], v[12:13], v[8:9] op_sel_hi:[1,0,1] neg_lo:[0,1,0] neg_hi:[0,1,0]
	s_waitcnt lgkmcnt(6)
	v_pk_mul_f32 v[10:11], v[2:3], v[34:35]
	v_pk_fma_f32 v[10:11], v[4:5], v[36:37], v[10:11]
	v_pk_mul_f32 v[14:15], v[2:3], v[184:185]
	v_add_f32_e32 v12, v10, v11
	v_pk_fma_f32 v[14:15], v[4:5], v[186:187], v[14:15]
	v_add_f32_e32 v102, v14, v15
	v_add_f32_dpp v12, v12, v12 quad_perm:[1,0,3,2] row_mask:0xf bank_mask:0xf bound_ctrl:1
	v_pk_mul_f32 v[6:7], v[30:31], v[118:119] op_sel:[0,1] op_sel_hi:[1,1]
	v_pk_mul_f32 v[8:9], v[32:33], v[118:119] op_sel:[0,1] op_sel_hi:[1,1]
	v_add_f32_dpp v12, v12, v12 quad_perm:[2,3,0,1] row_mask:0xf bank_mask:0xf bound_ctrl:1
	v_pk_fma_f32 v[6:7], v[2:3], v[22:23], v[6:7]
	v_pk_fma_f32 v[8:9], v[4:5], v[24:25], v[8:9]
	v_add_f32_dpp v12, v12, v12 row_half_mirror row_mask:0xf bank_mask:0xf bound_ctrl:1
	ds_read_b128 v[156:159], v84 offset:7488
	ds_read_b128 v[144:147], v84 offset:6720
	v_add_f32_dpp v12, v12, v12 row_mirror row_mask:0xf bank_mask:0xf bound_ctrl:1
	ds_read_b128 v[152:155], v84 offset:7232
	ds_read_b128 v[148:151], v84 offset:6976
	ds_read_b128 v[160:163], v84 offset:7744
	v_pk_fma_f32 v[2:3], v[26:27], v[12:13], v[6:7] op_sel_hi:[1,0,1] neg_lo:[0,1,0] neg_hi:[0,1,0]
	v_pk_fma_f32 v[4:5], v[28:29], v[12:13], v[8:9] op_sel_hi:[1,0,1] neg_lo:[0,1,0] neg_hi:[0,1,0]
	s_waitcnt lgkmcnt(5)
; #define LAS __attribute__((address_space(3)))
; __device__ __forceinline__ float row16_sum(float v) { v += dpp_f<0xB1>(v); v += dpp_f<0x4E>(v); v += dpp_f<0x141>(v); v += dpp_f<0x140>(v); return v; }
; __device__ __forceinline__ void rwkv_scan_unit(LAS unsigned char* lds, const float* Wd, const float* V, const bf16_t* RKKB, float* Yraw, int p, int rg, int tid) {
;     ...
;             for (int st = 0; st < SCAN_CH; ++st) {
;                 f32x4 wn = w, bn = b, kn = k, kkn = kk, rn = r; float vn = v;
;                 if (st + 1 < SCAN_CH) { const int o = (st + 1) * SCAN_STEP_B;
;                     wn = *(LAS const f32x4*)(sl + o); bn = *(LAS const f32x4*)(sl + o + 256); kn = *(LAS const f32x4*)(sl + o + 512); kkn = *(LAS const f32x4*)(sl + o + 768); rn = *(LAS const f32x4*)(sl + o + 1024);
;                     vn = *(LAS const float*)(vl + o); }
;                 float sa = (S[0] * kk[0] + S[1] * kk[1]) + (S[2] * kk[2] + S[3] * kk[3]);
;                 const f32x4 kvt = k * v;
;                 sa = -row16_sum(sa);
;                 S = S * w + (b * sa + kvt);
;                 yp[st & 15] = (S[0] * r[0] + S[1] * r[1]) + (S[2] * r[2] + S[3] * r[3]);
;                 if ((st & 15) == 15) yo[(size_t)(st - 15) * 64] = tr16_sum(yp, kq);
	v_pk_mul_f32 v[10:11], v[2:3], v[132:133]
	v_pk_fma_f32 v[10:11], v[4:5], v[134:135], v[10:11]
	v_pk_mul_f32 v[14:15], v[2:3], v[38:39]
	v_add_f32_e32 v12, v10, v11
	v_pk_fma_f32 v[14:15], v[4:5], v[40:41], v[14:15]
	v_add_f32_e32 v103, v14, v15
	v_add_f32_dpp v12, v12, v12 quad_perm:[1,0,3,2] row_mask:0xf bank_mask:0xf bound_ctrl:1
	v_pk_mul_f32 v[6:7], v[128:129], v[92:93] op_sel_hi:[1,0]
	v_pk_mul_f32 v[8:9], v[130:131], v[92:93] op_sel_hi:[1,0]
	v_add_f32_dpp v12, v12, v12 quad_perm:[2,3,0,1] row_mask:0xf bank_mask:0xf bound_ctrl:1
	v_pk_fma_f32 v[6:7], v[2:3], v[120:121], v[6:7]
	v_pk_fma_f32 v[8:9], v[4:5], v[122:123], v[8:9]
	v_add_f32_dpp v12, v12, v12 row_half_mirror row_mask:0xf bank_mask:0xf bound_ctrl:1
	ds_read_b128 v[180:183], v84 offset:8832
	ds_read_b128 v[168:171], v84 offset:8064
	v_add_f32_dpp v12, v12, v12 row_mirror row_mask:0xf bank_mask:0xf bound_ctrl:1
	ds_read_b128 v[176:179], v84 offset:8576
	ds_read_b128 v[172:175], v84 offset:8320
	ds_read_b128 v[184:187], v84 offset:9088
	v_pk_fma_f32 v[2:3], v[124:125], v[12:13], v[6:7] op_sel_hi:[1,0,1] neg_lo:[0,1,0] neg_hi:[0,1,0]
	v_pk_fma_f32 v[4:5], v[126:127], v[12:13], v[8:9] op_sel_hi:[1,0,1] neg_lo:[0,1,0] neg_hi:[0,1,0]
	s_waitcnt lgkmcnt(5)
	v_pk_mul_f32 v[10:11], v[2:3], v[156:157]
	v_pk_fma_f32 v[10:11], v[4:5], v[158:159], v[10:11]
	v_pk_mul_f32 v[14:15], v[2:3], v[136:137]
	v_add_f32_e32 v12, v10, v11
	v_pk_fma_f32 v[14:15], v[4:5], v[138:139], v[14:15]
	v_add_f32_e32 v104, v14, v15
	v_add_f32_dpp v12, v12, v12 quad_perm:[1,0,3,2] row_mask:0xf bank_mask:0xf bound_ctrl:1
	v_pk_mul_f32 v[6:7], v[152:153], v[92:93] op_sel:[0,1] op_sel_hi:[1,1]
	v_pk_mul_f32 v[8:9], v[154:155], v[92:93] op_sel:[0,1] op_sel_hi:[1,1]
	v_add_f32_dpp v12, v12, v12 quad_perm:[2,3,0,1] row_mask:0xf bank_mask:0xf bound_ctrl:1
	v_pk_fma_f32 v[6:7], v[2:3], v[144:145], v[6:7]
	v_pk_fma_f32 v[8:9], v[4:5], v[146:147], v[8:9]
	v_add_f32_dpp v12, v12, v12 row_half_mirror row_mask:0xf bank_mask:0xf bound_ctrl:1
	ds_read_b128 v[34:37], v84 offset:10176
	ds_read_b128 v[22:25], v84 offset:9408
	v_add_f32_dpp v12, v12, v12 row_mirror row_mask:0xf bank_mask:0xf bound_ctrl:1
	ds_read_b128 v[30:33], v84 offset:9920
	ds_read_b128 v[26:29], v84 offset:9664
	ds_read_b128 v[38:41], v84 offset:10432
	v_pk_fma_f32 v[2:3], v[148:149], v[12:13], v[6:7] op_sel_hi:[1,0,1] neg_lo:[0,1,0] neg_hi:[0,1,0]
	v_pk_fma_f32 v[4:5], v[150:151], v[12:13], v[8:9] op_sel_hi:[1,0,1] neg_lo:[0,1,0] neg_hi:[0,1,0]
	s_waitcnt lgkmcnt(5)
	v_pk_mul_f32 v[10:11], v[2:3], v[180:181]
	v_pk_fma_f32 v[10:11], v[4:5], v[182:183], v[10:11]
	v_pk_mul_f32 v[14:15], v[2:3], v[160:161]
	v_add_f32_e32 v12, v10, v11
	v_pk_fma_f32 v[14:15], v[4:5], v[162:163], v[14:15]
	v_add_f32_e32 v105, v14, v15
	v_add_f32_dpp v12, v12, v12 quad_perm:[1,0,3,2] row_mask:0xf bank_mask:0xf bound_ctrl:1
	v_pk_mul_f32 v[6:7], v[176:177], v[94:95] op_sel_hi:[1,0]
	v_pk_mul_f32 v[8:9], v[178:179], v[94:95] op_sel_hi:[1,0]
	v_add_f32_dpp v12, v12, v12 quad_perm:[2,3,0,1] row_mask:0xf bank_mask:0xf bound_ctrl:1
	v_pk_fma_f32 v[6:7], v[2:3], v[168:169], v[6:7]
	v_pk_fma_f32 v[8:9], v[4:5], v[170:171], v[8:9]
	v_add_f32_dpp v12, v12, v12 row_half_mirror row_mask:0xf bank_mask:0xf bound_ctrl:1
	ds_read_b128 v[132:135], v84 offset:11520
	ds_read_b128 v[120:123], v84 offset:10752
	v_add_f32_dpp v12, v12, v12 row_mirror row_mask:0xf bank_mask:0xf bound_ctrl:1
	ds_read_b128 v[128:131], v84 offset:11264
	ds_read_b128 v[116:119], v96 offset:32
	ds_read_b128 v[124:127], v84 offset:11008
	ds_read_b128 v[136:139], v84 offset:11776
	v_pk_fma_f32 v[2:3], v[172:173], v[12:13], v[6:7] op_sel_hi:[1,0,1] neg_lo:[0,1,0] neg_hi:[0,1,0]
	v_pk_fma_f32 v[4:5], v[174:175], v[12:13], v[8:9] op_sel_hi:[1,0,1] neg_lo:[0,1,0] neg_hi:[0,1,0]
	s_waitcnt lgkmcnt(6)
	v_pk_mul_f32 v[10:11], v[2:3], v[34:35]
	v_pk_fma_f32 v[10:11], v[4:5], v[36:37], v[10:11]
	v_pk_mul_f32 v[14:15], v[2:3], v[184:185]
	v_add_f32_e32 v12, v10, v11
	v_pk_fma_f32 v[14:15], v[4:5], v[186:187], v[14:15]
	v_add_f32_e32 v106, v14, v15
	v_add_f32_dpp v12, v12, v12 quad_perm:[1,0,3,2] row_mask:0xf bank_mask:0xf bound_ctrl:1
	v_pk_mul_f32 v[6:7], v[30:31], v[94:95] op_sel:[0,1] op_sel_hi:[1,1]
	v_pk_mul_f32 v[8:9], v[32:33], v[94:95] op_sel:[0,1] op_sel_hi:[1,1]
	v_add_f32_dpp v12, v12, v12 quad_perm:[2,3,0,1] row_mask:0xf bank_mask:0xf bound_ctrl:1
	v_pk_fma_f32 v[6:7], v[2:3], v[22:23], v[6:7]
	v_pk_fma_f32 v[8:9], v[4:5], v[24:25], v[8:9]
	v_add_f32_dpp v12, v12, v12 row_half_mirror row_mask:0xf bank_mask:0xf bound_ctrl:1
	ds_read_b128 v[156:159], v84 offset:12864
	ds_read_b128 v[144:147], v84 offset:12096
	v_add_f32_dpp v12, v12, v12 row_mirror row_mask:0xf bank_mask:0xf bound_ctrl:1
	ds_read_b128 v[152:155], v84 offset:12608
	ds_read_b128 v[148:151], v84 offset:12352
	ds_read_b128 v[160:163], v84 offset:13120
	v_pk_fma_f32 v[2:3], v[26:27], v[12:13], v[6:7] op_sel_hi:[1,0,1] neg_lo:[0,1,0] neg_hi:[0,1,0]
	v_pk_fma_f32 v[4:5], v[28:29], v[12:13], v[8:9] op_sel_hi:[1,0,1] neg_lo:[0,1,0] neg_hi:[0,1,0]
	s_waitcnt lgkmcnt(5)
; #define LAS __attribute__((address_space(3)))
; template <int CTRL> __device__ __forceinline__ float dpp_f(float v) { return __int_as_float(__builtin_amdgcn_update_dpp(0, __float_as_int(v), CTRL, 0xf, 0xf, true)); }
; __device__ __forceinline__ float row16_sum(float v) { v += dpp_f<0xB1>(v); v += dpp_f<0x4E>(v); v += dpp_f<0x141>(v); v += dpp_f<0x140>(v); return v; }
; __device__ __forceinline__ float tr16_sum(const float (&p)[16], int kq) {
;     const bool b3 = (kq & 8) != 0, b2 = (kq & 4) != 0, b1 = (kq & 2) != 0, b0 = (kq & 1) != 0;
;     float q[8], r[4], u[2];
; #pragma unroll
;     for (int t = 0; t < 8; ++t) { const float keep = b3 ? p[t + 8] : p[t], send = b3 ? p[t] : p[t + 8]; q[t] = keep + dpp_f<0x140>(send); }
; #pragma unroll
;     for (int t = 0; t < 4; ++t) { const float keep = b2 ? q[t + 4] : q[t], send = b2 ? q[t] : q[t + 4]; r[t] = keep + dpp_f<0x141>(send); }
; #pragma unroll
;     for (int t = 0; t < 2; ++t) { const float keep = b1 ? r[t + 2] : r[t], send = b1 ? r[t] : r[t + 2]; u[t] = keep + dpp_f<0x4E>(send); }
;     const float keep = b0 ? u[1] : u[0], send = b0 ? u[0] : u[1];
;     return keep + dpp_f<0xB1>(send);
; __device__ __forceinline__ void rwkv_scan_unit(LAS unsigned char* lds, const float* Wd, const float* V, const bf16_t* RKKB, float* Yraw, int p, int rg, int tid) {
;     ...
;             for (int st = 0; st < SCAN_CH; ++st) {
;                 f32x4 wn = w, bn = b, kn = k, kkn = kk, rn = r; float vn = v;
;                 if (st + 1 < SCAN_CH) { const int o = (st + 1) * SCAN_STEP_B;
;                     wn = *(LAS const f32x4*)(sl + o); bn = *(LAS const f32x4*)(sl + o + 256); kn = *(LAS const f32x4*)(sl + o + 512); kkn = *(LAS const f32x4*)(sl + o + 768); rn = *(LAS const f32x4*)(sl + o + 1024);
;                     vn = *(LAS const float*)(vl + o); }
;                 float sa = (S[0] * kk[0] + S[1] * kk[1]) + (S[2] * kk[2] + S[3] * kk[3]);
;                 const f32x4 kvt = k * v;
;                 sa = -row16_sum(sa);
;                 S = S * w + (b * sa + kvt);
;                 yp[st & 15] = (S[0] * r[0] + S[1] * r[1]) + (S[2] * r[2] + S[3] * r[3]);
;                 if ((st & 15) == 15) yo[(size_t)(st - 15) * 64] = tr16_sum(yp, kq);
	v_pk_mul_f32 v[10:11], v[2:3], v[132:133]
	v_pk_fma_f32 v[10:11], v[4:5], v[134:135], v[10:11]
	v_pk_mul_f32 v[14:15], v[2:3], v[38:39]
	v_add_f32_e32 v12, v10, v11
	v_pk_fma_f32 v[14:15], v[4:5], v[40:41], v[14:15]
	v_add_f32_e32 v107, v14, v15
	v_add_f32_dpp v12, v12, v12 quad_perm:[1,0,3,2] row_mask:0xf bank_mask:0xf bound_ctrl:1
	v_pk_mul_f32 v[6:7], v[128:129], v[116:117] op_sel_hi:[1,0]
	v_pk_mul_f32 v[8:9], v[130:131], v[116:117] op_sel_hi:[1,0]
	v_add_f32_dpp v12, v12, v12 quad_perm:[2,3,0,1] row_mask:0xf bank_mask:0xf bound_ctrl:1
	v_pk_fma_f32 v[6:7], v[2:3], v[120:121], v[6:7]
	v_pk_fma_f32 v[8:9], v[4:5], v[122:123], v[8:9]
	v_add_f32_dpp v12, v12, v12 row_half_mirror row_mask:0xf bank_mask:0xf bound_ctrl:1
	ds_read_b128 v[180:183], v84 offset:14208
	ds_read_b128 v[168:171], v84 offset:13440
	v_add_f32_dpp v12, v12, v12 row_mirror row_mask:0xf bank_mask:0xf bound_ctrl:1
	ds_read_b128 v[176:179], v84 offset:13952
	ds_read_b128 v[172:175], v84 offset:13696
	ds_read_b128 v[184:187], v84 offset:14464
	v_pk_fma_f32 v[2:3], v[124:125], v[12:13], v[6:7] op_sel_hi:[1,0,1] neg_lo:[0,1,0] neg_hi:[0,1,0]
	v_pk_fma_f32 v[4:5], v[126:127], v[12:13], v[8:9] op_sel_hi:[1,0,1] neg_lo:[0,1,0] neg_hi:[0,1,0]
	s_waitcnt lgkmcnt(5)
	v_pk_mul_f32 v[10:11], v[2:3], v[156:157]
	v_pk_fma_f32 v[10:11], v[4:5], v[158:159], v[10:11]
	v_pk_mul_f32 v[14:15], v[2:3], v[136:137]
	v_add_f32_e32 v12, v10, v11
	v_pk_fma_f32 v[14:15], v[4:5], v[138:139], v[14:15]
	v_add_f32_e32 v44, v14, v15
	v_add_f32_dpp v12, v12, v12 quad_perm:[1,0,3,2] row_mask:0xf bank_mask:0xf bound_ctrl:1
	v_add_f32_dpp v100, v100, v100 row_mirror row_mask:0xf bank_mask:0x3 bound_ctrl:1
	v_add_f32_dpp v100, v44, v44 row_mirror row_mask:0xf bank_mask:0xc bound_ctrl:1
	v_add_f32_dpp v12, v12, v12 quad_perm:[2,3,0,1] row_mask:0xf bank_mask:0xf bound_ctrl:1
	v_pk_mul_f32 v[6:7], v[152:153], v[116:117] op_sel:[0,1] op_sel_hi:[1,1]
	v_pk_mul_f32 v[8:9], v[154:155], v[116:117] op_sel:[0,1] op_sel_hi:[1,1]
	v_add_f32_dpp v12, v12, v12 row_half_mirror row_mask:0xf bank_mask:0xf bound_ctrl:1
	v_pk_fma_f32 v[6:7], v[2:3], v[144:145], v[6:7]
	v_pk_fma_f32 v[8:9], v[4:5], v[146:147], v[8:9]
	v_add_f32_dpp v12, v12, v12 row_mirror row_mask:0xf bank_mask:0xf bound_ctrl:1
	ds_read_b128 v[34:37], v84 offset:15552
	ds_read_b128 v[22:25], v84 offset:14784
	ds_read_b128 v[30:33], v84 offset:15296
	ds_read_b128 v[26:29], v84 offset:15040
	ds_read_b128 v[38:41], v84 offset:15808
	v_pk_fma_f32 v[2:3], v[148:149], v[12:13], v[6:7] op_sel_hi:[1,0,1] neg_lo:[0,1,0] neg_hi:[0,1,0]
	v_pk_fma_f32 v[4:5], v[150:151], v[12:13], v[8:9] op_sel_hi:[1,0,1] neg_lo:[0,1,0] neg_hi:[0,1,0]
	s_waitcnt lgkmcnt(5)
	v_pk_mul_f32 v[10:11], v[2:3], v[180:181]
	v_pk_fma_f32 v[10:11], v[4:5], v[182:183], v[10:11]
	v_pk_mul_f32 v[14:15], v[2:3], v[160:161]
	v_add_f32_e32 v12, v10, v11
	v_pk_fma_f32 v[14:15], v[4:5], v[162:163], v[14:15]
	v_add_f32_e32 v44, v14, v15
	v_add_f32_dpp v12, v12, v12 quad_perm:[1,0,3,2] row_mask:0xf bank_mask:0xf bound_ctrl:1
	v_add_f32_dpp v101, v101, v101 row_mirror row_mask:0xf bank_mask:0x3 bound_ctrl:1
	v_add_f32_dpp v101, v44, v44 row_mirror row_mask:0xf bank_mask:0xc bound_ctrl:1
	v_add_f32_dpp v12, v12, v12 quad_perm:[2,3,0,1] row_mask:0xf bank_mask:0xf bound_ctrl:1
	v_pk_mul_f32 v[6:7], v[176:177], v[118:119] op_sel_hi:[1,0]
	v_pk_mul_f32 v[8:9], v[178:179], v[118:119] op_sel_hi:[1,0]
	v_add_f32_dpp v12, v12, v12 row_half_mirror row_mask:0xf bank_mask:0xf bound_ctrl:1
	v_pk_fma_f32 v[6:7], v[2:3], v[168:169], v[6:7]
	v_pk_fma_f32 v[8:9], v[4:5], v[170:171], v[8:9]
	v_add_f32_dpp v12, v12, v12 row_mirror row_mask:0xf bank_mask:0xf bound_ctrl:1
	ds_read_b128 v[132:135], v84 offset:16896
	ds_read_b128 v[120:123], v84 offset:16128
	ds_read_b128 v[128:131], v84 offset:16640
	ds_read_b128 v[92:95], v96 offset:48
	ds_read_b128 v[124:127], v84 offset:16384
	ds_read_b128 v[136:139], v84 offset:17152
	v_pk_fma_f32 v[2:3], v[172:173], v[12:13], v[6:7] op_sel_hi:[1,0,1] neg_lo:[0,1,0] neg_hi:[0,1,0]
	v_pk_fma_f32 v[4:5], v[174:175], v[12:13], v[8:9] op_sel_hi:[1,0,1] neg_lo:[0,1,0] neg_hi:[0,1,0]
	s_waitcnt lgkmcnt(6)
	v_pk_mul_f32 v[10:11], v[2:3], v[34:35]
	v_pk_fma_f32 v[10:11], v[4:5], v[36:37], v[10:11]
	v_pk_mul_f32 v[14:15], v[2:3], v[184:185]
	v_add_f32_e32 v12, v10, v11
	v_pk_fma_f32 v[14:15], v[4:5], v[186:187], v[14:15]
	v_add_f32_e32 v44, v14, v15
	v_add_f32_dpp v12, v12, v12 quad_perm:[1,0,3,2] row_mask:0xf bank_mask:0xf bound_ctrl:1
	v_add_f32_dpp v102, v102, v102 row_mirror row_mask:0xf bank_mask:0x3 bound_ctrl:1
	v_add_f32_dpp v102, v44, v44 row_mirror row_mask:0xf bank_mask:0xc bound_ctrl:1
	v_add_f32_dpp v12, v12, v12 quad_perm:[2,3,0,1] row_mask:0xf bank_mask:0xf bound_ctrl:1
	v_pk_mul_f32 v[6:7], v[30:31], v[118:119] op_sel:[0,1] op_sel_hi:[1,1]
	v_pk_mul_f32 v[8:9], v[32:33], v[118:119] op_sel:[0,1] op_sel_hi:[1,1]
	v_add_f32_dpp v12, v12, v12 row_half_mirror row_mask:0xf bank_mask:0xf bound_ctrl:1
	v_pk_fma_f32 v[6:7], v[2:3], v[22:23], v[6:7]
	v_pk_fma_f32 v[8:9], v[4:5], v[24:25], v[8:9]
	v_add_f32_dpp v12, v12, v12 row_mirror row_mask:0xf bank_mask:0xf bound_ctrl:1
	ds_read_b128 v[156:159], v84 offset:18240
	ds_read_b128 v[144:147], v84 offset:17472
	ds_read_b128 v[152:155], v84 offset:17984
	ds_read_b128 v[148:151], v84 offset:17728
	ds_read_b128 v[160:163], v84 offset:18496
	v_pk_fma_f32 v[2:3], v[26:27], v[12:13], v[6:7] op_sel_hi:[1,0,1] neg_lo:[0,1,0] neg_hi:[0,1,0]
	v_pk_fma_f32 v[4:5], v[28:29], v[12:13], v[8:9] op_sel_hi:[1,0,1] neg_lo:[0,1,0] neg_hi:[0,1,0]
	s_waitcnt lgkmcnt(5)
; #define LAS __attribute__((address_space(3)))
; template <int CTRL> __device__ __forceinline__ float dpp_f(float v) { return __int_as_float(__builtin_amdgcn_update_dpp(0, __float_as_int(v), CTRL, 0xf, 0xf, true)); }
; __device__ __forceinline__ float row16_sum(float v) { v += dpp_f<0xB1>(v); v += dpp_f<0x4E>(v); v += dpp_f<0x141>(v); v += dpp_f<0x140>(v); return v; }
; __device__ __forceinline__ float tr16_sum(const float (&p)[16], int kq) {
;     const bool b3 = (kq & 8) != 0, b2 = (kq & 4) != 0, b1 = (kq & 2) != 0, b0 = (kq & 1) != 0;
;     float q[8], r[4], u[2];
; #pragma unroll
;     for (int t = 0; t < 8; ++t) { const float keep = b3 ? p[t + 8] : p[t], send = b3 ? p[t] : p[t + 8]; q[t] = keep + dpp_f<0x140>(send); }
; #pragma unroll
;     for (int t = 0; t < 4; ++t) { const float keep = b2 ? q[t + 4] : q[t], send = b2 ? q[t] : q[t + 4]; r[t] = keep + dpp_f<0x141>(send); }
; #pragma unroll
;     for (int t = 0; t < 2; ++t) { const float keep = b1 ? r[t + 2] : r[t], send = b1 ? r[t] : r[t + 2]; u[t] = keep + dpp_f<0x4E>(send); }
;     const float keep = b0 ? u[1] : u[0], send = b0 ? u[0] : u[1];
;     return keep + dpp_f<0xB1>(send);
; __device__ __forceinline__ void rwkv_scan_unit(LAS unsigned char* lds, const float* Wd, const float* V, const bf16_t* RKKB, float* Yraw, int p, int rg, int tid) {
;     ...
;             for (int st = 0; st < SCAN_CH; ++st) {
;                 f32x4 wn = w, bn = b, kn = k, kkn = kk, rn = r; float vn = v;
;                 if (st + 1 < SCAN_CH) { const int o = (st + 1) * SCAN_STEP_B;
;                     wn = *(LAS const f32x4*)(sl + o); bn = *(LAS const f32x4*)(sl + o + 256); kn = *(LAS const f32x4*)(sl + o + 512); kkn = *(LAS const f32x4*)(sl + o + 768); rn = *(LAS const f32x4*)(sl + o + 1024);
;                     vn = *(LAS const float*)(vl + o); }
;                 float sa = (S[0] * kk[0] + S[1] * kk[1]) + (S[2] * kk[2] + S[3] * kk[3]);
;                 const f32x4 kvt = k * v;
;                 sa = -row16_sum(sa);
;                 S = S * w + (b * sa + kvt);
;                 yp[st & 15] = (S[0] * r[0] + S[1] * r[1]) + (S[2] * r[2] + S[3] * r[3]);
;                 if ((st & 15) == 15) yo[(size_t)(st - 15) * 64] = tr16_sum(yp, kq);
	v_pk_mul_f32 v[10:11], v[2:3], v[132:133]
	v_pk_fma_f32 v[10:11], v[4:5], v[134:135], v[10:11]
	v_pk_mul_f32 v[14:15], v[2:3], v[38:39]
	v_add_f32_e32 v12, v10, v11
	v_pk_fma_f32 v[14:15], v[4:5], v[40:41], v[14:15]
	v_add_f32_e32 v44, v14, v15
	v_add_f32_dpp v12, v12, v12 quad_perm:[1,0,3,2] row_mask:0xf bank_mask:0xf bound_ctrl:1
	v_add_f32_dpp v103, v103, v103 row_mirror row_mask:0xf bank_mask:0x3 bound_ctrl:1
	v_add_f32_dpp v103, v44, v44 row_mirror row_mask:0xf bank_mask:0xc bound_ctrl:1
	v_add_f32_dpp v12, v12, v12 quad_perm:[2,3,0,1] row_mask:0xf bank_mask:0xf bound_ctrl:1
	v_pk_mul_f32 v[6:7], v[128:129], v[92:93] op_sel_hi:[1,0]
	v_pk_mul_f32 v[8:9], v[130:131], v[92:93] op_sel_hi:[1,0]
	v_add_f32_dpp v12, v12, v12 row_half_mirror row_mask:0xf bank_mask:0xf bound_ctrl:1
	v_pk_fma_f32 v[6:7], v[2:3], v[120:121], v[6:7]
	v_pk_fma_f32 v[8:9], v[4:5], v[122:123], v[8:9]
	v_add_f32_dpp v12, v12, v12 row_mirror row_mask:0xf bank_mask:0xf bound_ctrl:1
	ds_read_b128 v[180:183], v84 offset:19584
	ds_read_b128 v[168:171], v84 offset:18816
	ds_read_b128 v[176:179], v84 offset:19328
	ds_read_b128 v[172:175], v84 offset:19072
	ds_read_b128 v[184:187], v84 offset:19840
	v_pk_fma_f32 v[2:3], v[124:125], v[12:13], v[6:7] op_sel_hi:[1,0,1] neg_lo:[0,1,0] neg_hi:[0,1,0]
	v_pk_fma_f32 v[4:5], v[126:127], v[12:13], v[8:9] op_sel_hi:[1,0,1] neg_lo:[0,1,0] neg_hi:[0,1,0]
	s_waitcnt lgkmcnt(5)
	v_pk_mul_f32 v[10:11], v[2:3], v[156:157]
	v_pk_fma_f32 v[10:11], v[4:5], v[158:159], v[10:11]
	v_pk_mul_f32 v[14:15], v[2:3], v[136:137]
	v_add_f32_e32 v12, v10, v11
	v_pk_fma_f32 v[14:15], v[4:5], v[138:139], v[14:15]
	v_add_f32_e32 v44, v14, v15
	v_add_f32_dpp v12, v12, v12 quad_perm:[1,0,3,2] row_mask:0xf bank_mask:0xf bound_ctrl:1
	v_add_f32_dpp v104, v104, v104 row_mirror row_mask:0xf bank_mask:0x3 bound_ctrl:1
	v_add_f32_dpp v104, v44, v44 row_mirror row_mask:0xf bank_mask:0xc bound_ctrl:1
	v_add_f32_dpp v12, v12, v12 quad_perm:[2,3,0,1] row_mask:0xf bank_mask:0xf bound_ctrl:1
	v_pk_mul_f32 v[6:7], v[152:153], v[92:93] op_sel:[0,1] op_sel_hi:[1,1]
	v_pk_mul_f32 v[8:9], v[154:155], v[92:93] op_sel:[0,1] op_sel_hi:[1,1]
	v_add_f32_dpp v12, v12, v12 row_half_mirror row_mask:0xf bank_mask:0xf bound_ctrl:1
	v_pk_fma_f32 v[6:7], v[2:3], v[144:145], v[6:7]
	v_pk_fma_f32 v[8:9], v[4:5], v[146:147], v[8:9]
	v_add_f32_dpp v12, v12, v12 row_mirror row_mask:0xf bank_mask:0xf bound_ctrl:1
	ds_read_b128 v[34:37], v84 offset:20928
	ds_read_b128 v[22:25], v84 offset:20160
	ds_read_b128 v[30:33], v84 offset:20672
	ds_read_b128 v[26:29], v84 offset:20416
	ds_read_b128 v[38:41], v84 offset:21184
	v_pk_fma_f32 v[2:3], v[148:149], v[12:13], v[6:7] op_sel_hi:[1,0,1] neg_lo:[0,1,0] neg_hi:[0,1,0]
	v_pk_fma_f32 v[4:5], v[150:151], v[12:13], v[8:9] op_sel_hi:[1,0,1] neg_lo:[0,1,0] neg_hi:[0,1,0]
	s_waitcnt lgkmcnt(5)
	v_pk_mul_f32 v[10:11], v[2:3], v[180:181]
	v_pk_fma_f32 v[10:11], v[4:5], v[182:183], v[10:11]
	v_pk_mul_f32 v[14:15], v[2:3], v[160:161]
	v_add_f32_e32 v12, v10, v11
	v_pk_fma_f32 v[14:15], v[4:5], v[162:163], v[14:15]
	v_add_f32_e32 v44, v14, v15
	v_add_f32_dpp v12, v12, v12 quad_perm:[1,0,3,2] row_mask:0xf bank_mask:0xf bound_ctrl:1
	v_add_f32_dpp v105, v105, v105 row_mirror row_mask:0xf bank_mask:0x3 bound_ctrl:1
	v_add_f32_dpp v105, v44, v44 row_mirror row_mask:0xf bank_mask:0xc bound_ctrl:1
	v_add_f32_dpp v12, v12, v12 quad_perm:[2,3,0,1] row_mask:0xf bank_mask:0xf bound_ctrl:1
	v_pk_mul_f32 v[6:7], v[176:177], v[94:95] op_sel_hi:[1,0]
	v_pk_mul_f32 v[8:9], v[178:179], v[94:95] op_sel_hi:[1,0]
	v_add_f32_dpp v12, v12, v12 row_half_mirror row_mask:0xf bank_mask:0xf bound_ctrl:1
	v_pk_fma_f32 v[6:7], v[2:3], v[168:169], v[6:7]
	v_pk_fma_f32 v[8:9], v[4:5], v[170:171], v[8:9]
	v_add_f32_dpp v12, v12, v12 row_mirror row_mask:0xf bank_mask:0xf bound_ctrl:1
	ds_read_b128 v[132:135], v84 offset:22272
	ds_read_b128 v[120:123], v84 offset:21504
	ds_read_b128 v[128:131], v84 offset:22016
	ds_read_b128 v[116:119], v96 offset:64
	ds_read_b128 v[124:127], v84 offset:21760
	ds_read_b128 v[136:139], v84 offset:22528
	v_pk_fma_f32 v[2:3], v[172:173], v[12:13], v[6:7] op_sel_hi:[1,0,1] neg_lo:[0,1,0] neg_hi:[0,1,0]
	v_pk_fma_f32 v[4:5], v[174:175], v[12:13], v[8:9] op_sel_hi:[1,0,1] neg_lo:[0,1,0] neg_hi:[0,1,0]
	s_waitcnt lgkmcnt(6)
	v_pk_mul_f32 v[10:11], v[2:3], v[34:35]
	v_pk_fma_f32 v[10:11], v[4:5], v[36:37], v[10:11]
	v_pk_mul_f32 v[14:15], v[2:3], v[184:185]
	v_add_f32_e32 v12, v10, v11
	v_pk_fma_f32 v[14:15], v[4:5], v[186:187], v[14:15]
	v_add_f32_e32 v44, v14, v15
	v_add_f32_dpp v12, v12, v12 quad_perm:[1,0,3,2] row_mask:0xf bank_mask:0xf bound_ctrl:1
	v_add_f32_dpp v106, v106, v106 row_mirror row_mask:0xf bank_mask:0x3 bound_ctrl:1
	v_add_f32_dpp v106, v44, v44 row_mirror row_mask:0xf bank_mask:0xc bound_ctrl:1
	v_add_f32_dpp v12, v12, v12 quad_perm:[2,3,0,1] row_mask:0xf bank_mask:0xf bound_ctrl:1
	v_pk_mul_f32 v[6:7], v[30:31], v[94:95] op_sel:[0,1] op_sel_hi:[1,1]
	v_pk_mul_f32 v[8:9], v[32:33], v[94:95] op_sel:[0,1] op_sel_hi:[1,1]
	v_add_f32_dpp v12, v12, v12 row_half_mirror row_mask:0xf bank_mask:0xf bound_ctrl:1
	v_pk_fma_f32 v[6:7], v[2:3], v[22:23], v[6:7]
	v_pk_fma_f32 v[8:9], v[4:5], v[24:25], v[8:9]
	v_add_f32_dpp v12, v12, v12 row_mirror row_mask:0xf bank_mask:0xf bound_ctrl:1
	ds_read_b128 v[156:159], v84 offset:23616
	ds_read_b128 v[144:147], v84 offset:22848
	ds_read_b128 v[152:155], v84 offset:23360
	ds_read_b128 v[148:151], v84 offset:23104
	ds_read_b128 v[160:163], v84 offset:23872
	v_pk_fma_f32 v[2:3], v[26:27], v[12:13], v[6:7] op_sel_hi:[1,0,1] neg_lo:[0,1,0] neg_hi:[0,1,0]
	v_pk_fma_f32 v[4:5], v[28:29], v[12:13], v[8:9] op_sel_hi:[1,0,1] neg_lo:[0,1,0] neg_hi:[0,1,0]
	s_waitcnt lgkmcnt(5)
; #define LAS __attribute__((address_space(3)))
; template <int CTRL> __device__ __forceinline__ float dpp_f(float v) { return __int_as_float(__builtin_amdgcn_update_dpp(0, __float_as_int(v), CTRL, 0xf, 0xf, true)); }
; __device__ __forceinline__ float row16_sum(float v) { v += dpp_f<0xB1>(v); v += dpp_f<0x4E>(v); v += dpp_f<0x141>(v); v += dpp_f<0x140>(v); return v; }
; __device__ __forceinline__ float tr16_sum(const float (&p)[16], int kq) {
;     const bool b3 = (kq & 8) != 0, b2 = (kq & 4) != 0, b1 = (kq & 2) != 0, b0 = (kq & 1) != 0;
;     float q[8], r[4], u[2];
; #pragma unroll
;     for (int t = 0; t < 8; ++t) { const float keep = b3 ? p[t + 8] : p[t], send = b3 ? p[t] : p[t + 8]; q[t] = keep + dpp_f<0x140>(send); }
; #pragma unroll
;     for (int t = 0; t < 4; ++t) { const float keep = b2 ? q[t + 4] : q[t], send = b2 ? q[t] : q[t + 4]; r[t] = keep + dpp_f<0x141>(send); }
; #pragma unroll
;     for (int t = 0; t < 2; ++t) { const float keep = b1 ? r[t + 2] : r[t], send = b1 ? r[t] : r[t + 2]; u[t] = keep + dpp_f<0x4E>(send); }
;     const float keep = b0 ? u[1] : u[0], send = b0 ? u[0] : u[1];
;     return keep + dpp_f<0xB1>(send);
; __device__ __forceinline__ void rwkv_scan_unit(LAS unsigned char* lds, const float* Wd, const float* V, const bf16_t* RKKB, float* Yraw, int p, int rg, int tid) {
;     ...
;             for (int st = 0; st < SCAN_CH; ++st) {
;                 f32x4 wn = w, bn = b, kn = k, kkn = kk, rn = r; float vn = v;
;                 if (st + 1 < SCAN_CH) { const int o = (st + 1) * SCAN_STEP_B;
;                     wn = *(LAS const f32x4*)(sl + o); bn = *(LAS const f32x4*)(sl + o + 256); kn = *(LAS const f32x4*)(sl + o + 512); kkn = *(LAS const f32x4*)(sl + o + 768); rn = *(LAS const f32x4*)(sl + o + 1024);
;                     vn = *(LAS const float*)(vl + o); }
;                 float sa = (S[0] * kk[0] + S[1] * kk[1]) + (S[2] * kk[2] + S[3] * kk[3]);
;                 const f32x4 kvt = k * v;
;                 sa = -row16_sum(sa);
;                 S = S * w + (b * sa + kvt);
;                 yp[st & 15] = (S[0] * r[0] + S[1] * r[1]) + (S[2] * r[2] + S[3] * r[3]);
;                 if ((st & 15) == 15) yo[(size_t)(st - 15) * 64] = tr16_sum(yp, kq);
	v_pk_mul_f32 v[10:11], v[2:3], v[132:133]
	v_pk_fma_f32 v[10:11], v[4:5], v[134:135], v[10:11]
	v_pk_mul_f32 v[14:15], v[2:3], v[38:39]
	v_add_f32_e32 v12, v10, v11
	v_pk_fma_f32 v[14:15], v[4:5], v[40:41], v[14:15]
	v_add_f32_e32 v44, v14, v15
	v_add_f32_dpp v107, v107, v107 row_mirror row_mask:0xf bank_mask:0x3 bound_ctrl:1
	s_nop 0
	v_add_f32_dpp v107, v44, v44 row_mirror row_mask:0xf bank_mask:0xc bound_ctrl:1
	v_add_f32_dpp v12, v12, v12 quad_perm:[1,0,3,2] row_mask:0xf bank_mask:0xf bound_ctrl:1
	v_pk_mul_f32 v[6:7], v[128:129], v[116:117] op_sel_hi:[1,0]
	v_pk_mul_f32 v[8:9], v[130:131], v[116:117] op_sel_hi:[1,0]
	v_pk_fma_f32 v[6:7], v[2:3], v[120:121], v[6:7]
	v_pk_fma_f32 v[8:9], v[4:5], v[122:123], v[8:9]
	v_add_f32_dpp v12, v12, v12 quad_perm:[2,3,0,1] row_mask:0xf bank_mask:0xf bound_ctrl:1
	ds_read_b128 v[180:183], v84 offset:24960
	ds_read_b128 v[168:171], v84 offset:24192
	ds_read_b128 v[176:179], v84 offset:24704
	ds_read_b128 v[172:175], v84 offset:24448
	v_add_f32_dpp v12, v12, v12 row_half_mirror row_mask:0xf bank_mask:0xf bound_ctrl:1
	ds_read_b128 v[184:187], v84 offset:25216
	v_add_f32_dpp v100, v100, v100 row_half_mirror row_mask:0xf bank_mask:0x5 bound_ctrl:1
	v_add_f32_dpp v100, v104, v104 row_half_mirror row_mask:0xf bank_mask:0xa bound_ctrl:1
	v_add_f32_dpp v101, v101, v101 row_half_mirror row_mask:0xf bank_mask:0x5 bound_ctrl:1
	v_add_f32_dpp v12, v12, v12 row_mirror row_mask:0xf bank_mask:0xf bound_ctrl:1
	v_add_f32_dpp v101, v105, v105 row_half_mirror row_mask:0xf bank_mask:0xa bound_ctrl:1
	v_add_f32_dpp v102, v102, v102 row_half_mirror row_mask:0xf bank_mask:0x5 bound_ctrl:1
	v_add_f32_dpp v102, v106, v106 row_half_mirror row_mask:0xf bank_mask:0xa bound_ctrl:1
	v_add_f32_dpp v103, v103, v103 row_half_mirror row_mask:0xf bank_mask:0x5 bound_ctrl:1
	v_add_f32_dpp v103, v107, v107 row_half_mirror row_mask:0xf bank_mask:0xa bound_ctrl:1
	v_cndmask_b32_e64 v16, v102, v100, s[8:9]
	v_pk_fma_f32 v[2:3], v[124:125], v[12:13], v[6:7] op_sel_hi:[1,0,1] neg_lo:[0,1,0] neg_hi:[0,1,0]
	v_pk_fma_f32 v[4:5], v[126:127], v[12:13], v[8:9] op_sel_hi:[1,0,1] neg_lo:[0,1,0] neg_hi:[0,1,0]
	s_waitcnt lgkmcnt(5)
	v_pk_mul_f32 v[10:11], v[2:3], v[156:157]
	v_pk_fma_f32 v[10:11], v[4:5], v[158:159], v[10:11]
	v_pk_mul_f32 v[14:15], v[2:3], v[136:137]
	v_add_f32_e32 v12, v10, v11
	v_pk_fma_f32 v[14:15], v[4:5], v[138:139], v[14:15]
	v_add_f32_e32 v108, v14, v15
	v_pk_mul_f32 v[6:7], v[152:153], v[116:117] op_sel:[0,1] op_sel_hi:[1,1]
	v_pk_mul_f32 v[8:9], v[154:155], v[116:117] op_sel:[0,1] op_sel_hi:[1,1]
	v_add_f32_dpp v12, v12, v12 quad_perm:[1,0,3,2] row_mask:0xf bank_mask:0xf bound_ctrl:1
	v_pk_fma_f32 v[6:7], v[2:3], v[144:145], v[6:7]
	v_pk_fma_f32 v[8:9], v[4:5], v[146:147], v[8:9]
	ds_read_b128 v[34:37], v84 offset:26304
	ds_read_b128 v[22:25], v84 offset:25536
	v_add_f32_dpp v12, v12, v12 quad_perm:[2,3,0,1] row_mask:0xf bank_mask:0xf bound_ctrl:1
	ds_read_b128 v[30:33], v84 offset:26048
	ds_read_b128 v[26:29], v84 offset:25792
	ds_read_b128 v[38:41], v84 offset:26560
	v_cndmask_b32_e64 v17, v100, v102, s[8:9]
	v_add_f32_dpp v12, v12, v12 row_half_mirror row_mask:0xf bank_mask:0xf bound_ctrl:1
	s_nop 0
	v_add_f32_dpp v16, v17, v16 quad_perm:[2,3,0,1] row_mask:0xf bank_mask:0xf bound_ctrl:1
	v_cndmask_b32_e64 v18, v103, v101, s[8:9]
	v_cndmask_b32_e64 v19, v101, v103, s[8:9]
	s_nop 1
	v_add_f32_dpp v18, v19, v18 quad_perm:[2,3,0,1] row_mask:0xf bank_mask:0xf bound_ctrl:1
	v_add_f32_dpp v12, v12, v12 row_mirror row_mask:0xf bank_mask:0xf bound_ctrl:1
	v_cndmask_b32_e64 v17, v18, v16, s[10:11]
	v_cndmask_b32_e64 v19, v16, v18, s[10:11]
	s_nop 1
	v_add_f32_dpp v17, v19, v17 quad_perm:[1,0,3,2] row_mask:0xf bank_mask:0xf bound_ctrl:1
	global_store_dword v[88:89], v17, off
	v_pk_fma_f32 v[2:3], v[148:149], v[12:13], v[6:7] op_sel_hi:[1,0,1] neg_lo:[0,1,0] neg_hi:[0,1,0]
	v_pk_fma_f32 v[4:5], v[150:151], v[12:13], v[8:9] op_sel_hi:[1,0,1] neg_lo:[0,1,0] neg_hi:[0,1,0]
	s_waitcnt lgkmcnt(5)
	v_pk_mul_f32 v[10:11], v[2:3], v[180:181]
	v_pk_fma_f32 v[10:11], v[4:5], v[182:183], v[10:11]
	v_pk_mul_f32 v[14:15], v[2:3], v[160:161]
	v_add_f32_e32 v12, v10, v11
	v_pk_fma_f32 v[14:15], v[4:5], v[162:163], v[14:15]
	v_add_f32_e32 v109, v14, v15
	v_add_f32_dpp v12, v12, v12 quad_perm:[1,0,3,2] row_mask:0xf bank_mask:0xf bound_ctrl:1
	v_pk_mul_f32 v[6:7], v[176:177], v[118:119] op_sel_hi:[1,0]
	v_pk_mul_f32 v[8:9], v[178:179], v[118:119] op_sel_hi:[1,0]
	v_add_f32_dpp v12, v12, v12 quad_perm:[2,3,0,1] row_mask:0xf bank_mask:0xf bound_ctrl:1
	v_pk_fma_f32 v[6:7], v[2:3], v[168:169], v[6:7]
	v_pk_fma_f32 v[8:9], v[4:5], v[170:171], v[8:9]
	v_add_f32_dpp v12, v12, v12 row_half_mirror row_mask:0xf bank_mask:0xf bound_ctrl:1
	ds_read_b128 v[132:135], v84 offset:27648
	ds_read_b128 v[120:123], v84 offset:26880
	v_add_f32_dpp v12, v12, v12 row_mirror row_mask:0xf bank_mask:0xf bound_ctrl:1
	ds_read_b128 v[128:131], v84 offset:27392
	ds_read_b128 v[92:95], v96 offset:80
	ds_read_b128 v[124:127], v84 offset:27136
	ds_read_b128 v[136:139], v84 offset:27904
	v_pk_fma_f32 v[2:3], v[172:173], v[12:13], v[6:7] op_sel_hi:[1,0,1] neg_lo:[0,1,0] neg_hi:[0,1,0]
	v_pk_fma_f32 v[4:5], v[174:175], v[12:13], v[8:9] op_sel_hi:[1,0,1] neg_lo:[0,1,0] neg_hi:[0,1,0]
	s_waitcnt lgkmcnt(6)
; #define LAS __attribute__((address_space(3)))
; __device__ __forceinline__ float row16_sum(float v) { v += dpp_f<0xB1>(v); v += dpp_f<0x4E>(v); v += dpp_f<0x141>(v); v += dpp_f<0x140>(v); return v; }
; __device__ __forceinline__ void rwkv_scan_unit(LAS unsigned char* lds, const float* Wd, const float* V, const bf16_t* RKKB, float* Yraw, int p, int rg, int tid) {
;     ...
;             for (int st = 0; st < SCAN_CH; ++st) {
;                 f32x4 wn = w, bn = b, kn = k, kkn = kk, rn = r; float vn = v;
;                 if (st + 1 < SCAN_CH) { const int o = (st + 1) * SCAN_STEP_B;
;                     wn = *(LAS const f32x4*)(sl + o); bn = *(LAS const f32x4*)(sl + o + 256); kn = *(LAS const f32x4*)(sl + o + 512); kkn = *(LAS const f32x4*)(sl + o + 768); rn = *(LAS const f32x4*)(sl + o + 1024);
;                     vn = *(LAS const float*)(vl + o); }
;                 float sa = (S[0] * kk[0] + S[1] * kk[1]) + (S[2] * kk[2] + S[3] * kk[3]);
;                 const f32x4 kvt = k * v;
;                 sa = -row16_sum(sa);
;                 S = S * w + (b * sa + kvt);
;                 yp[st & 15] = (S[0] * r[0] + S[1] * r[1]) + (S[2] * r[2] + S[3] * r[3]);
;                 if ((st & 15) == 15) yo[(size_t)(st - 15) * 64] = tr16_sum(yp, kq);
	v_pk_mul_f32 v[10:11], v[2:3], v[34:35]
	v_pk_fma_f32 v[10:11], v[4:5], v[36:37], v[10:11]
	v_pk_mul_f32 v[14:15], v[2:3], v[184:185]
	v_add_f32_e32 v12, v10, v11
	v_pk_fma_f32 v[14:15], v[4:5], v[186:187], v[14:15]
	v_add_f32_e32 v110, v14, v15
	v_add_f32_dpp v12, v12, v12 quad_perm:[1,0,3,2] row_mask:0xf bank_mask:0xf bound_ctrl:1
	v_pk_mul_f32 v[6:7], v[30:31], v[118:119] op_sel:[0,1] op_sel_hi:[1,1]
	v_pk_mul_f32 v[8:9], v[32:33], v[118:119] op_sel:[0,1] op_sel_hi:[1,1]
	v_add_f32_dpp v12, v12, v12 quad_perm:[2,3,0,1] row_mask:0xf bank_mask:0xf bound_ctrl:1
	v_pk_fma_f32 v[6:7], v[2:3], v[22:23], v[6:7]
	v_pk_fma_f32 v[8:9], v[4:5], v[24:25], v[8:9]
	v_add_f32_dpp v12, v12, v12 row_half_mirror row_mask:0xf bank_mask:0xf bound_ctrl:1
	ds_read_b128 v[156:159], v84 offset:28992
	ds_read_b128 v[144:147], v84 offset:28224
	v_add_f32_dpp v12, v12, v12 row_mirror row_mask:0xf bank_mask:0xf bound_ctrl:1
	ds_read_b128 v[152:155], v84 offset:28736
	ds_read_b128 v[148:151], v84 offset:28480
	ds_read_b128 v[160:163], v84 offset:29248
	v_pk_fma_f32 v[2:3], v[26:27], v[12:13], v[6:7] op_sel_hi:[1,0,1] neg_lo:[0,1,0] neg_hi:[0,1,0]
	v_pk_fma_f32 v[4:5], v[28:29], v[12:13], v[8:9] op_sel_hi:[1,0,1] neg_lo:[0,1,0] neg_hi:[0,1,0]
	s_waitcnt lgkmcnt(5)
	v_pk_mul_f32 v[10:11], v[2:3], v[132:133]
	v_pk_fma_f32 v[10:11], v[4:5], v[134:135], v[10:11]
	v_pk_mul_f32 v[14:15], v[2:3], v[38:39]
	v_add_f32_e32 v12, v10, v11
	v_pk_fma_f32 v[14:15], v[4:5], v[40:41], v[14:15]
	v_add_f32_e32 v111, v14, v15
	v_add_f32_dpp v12, v12, v12 quad_perm:[1,0,3,2] row_mask:0xf bank_mask:0xf bound_ctrl:1
	v_pk_mul_f32 v[6:7], v[128:129], v[92:93] op_sel_hi:[1,0]
	v_pk_mul_f32 v[8:9], v[130:131], v[92:93] op_sel_hi:[1,0]
	v_add_f32_dpp v12, v12, v12 quad_perm:[2,3,0,1] row_mask:0xf bank_mask:0xf bound_ctrl:1
	v_pk_fma_f32 v[6:7], v[2:3], v[120:121], v[6:7]
	v_pk_fma_f32 v[8:9], v[4:5], v[122:123], v[8:9]
	v_add_f32_dpp v12, v12, v12 row_half_mirror row_mask:0xf bank_mask:0xf bound_ctrl:1
	ds_read_b128 v[180:183], v84 offset:30336
	ds_read_b128 v[168:171], v84 offset:29568
	v_add_f32_dpp v12, v12, v12 row_mirror row_mask:0xf bank_mask:0xf bound_ctrl:1
	ds_read_b128 v[176:179], v84 offset:30080
	ds_read_b128 v[172:175], v84 offset:29824
	ds_read_b128 v[184:187], v84 offset:30592
	v_pk_fma_f32 v[2:3], v[124:125], v[12:13], v[6:7] op_sel_hi:[1,0,1] neg_lo:[0,1,0] neg_hi:[0,1,0]
	v_pk_fma_f32 v[4:5], v[126:127], v[12:13], v[8:9] op_sel_hi:[1,0,1] neg_lo:[0,1,0] neg_hi:[0,1,0]
	s_waitcnt lgkmcnt(5)
	v_pk_mul_f32 v[10:11], v[2:3], v[156:157]
	v_pk_fma_f32 v[10:11], v[4:5], v[158:159], v[10:11]
	v_pk_mul_f32 v[14:15], v[2:3], v[136:137]
	v_add_f32_e32 v12, v10, v11
	v_pk_fma_f32 v[14:15], v[4:5], v[138:139], v[14:15]
	v_add_f32_e32 v112, v14, v15
	v_add_f32_dpp v12, v12, v12 quad_perm:[1,0,3,2] row_mask:0xf bank_mask:0xf bound_ctrl:1
	v_pk_mul_f32 v[6:7], v[152:153], v[92:93] op_sel:[0,1] op_sel_hi:[1,1]
	v_pk_mul_f32 v[8:9], v[154:155], v[92:93] op_sel:[0,1] op_sel_hi:[1,1]
	v_add_f32_dpp v12, v12, v12 quad_perm:[2,3,0,1] row_mask:0xf bank_mask:0xf bound_ctrl:1
	v_pk_fma_f32 v[6:7], v[2:3], v[144:145], v[6:7]
	v_pk_fma_f32 v[8:9], v[4:5], v[146:147], v[8:9]
	v_add_f32_dpp v12, v12, v12 row_half_mirror row_mask:0xf bank_mask:0xf bound_ctrl:1
	ds_read_b128 v[34:37], v84 offset:31680
	ds_read_b128 v[22:25], v84 offset:30912
	v_add_f32_dpp v12, v12, v12 row_mirror row_mask:0xf bank_mask:0xf bound_ctrl:1
	ds_read_b128 v[30:33], v84 offset:31424
	ds_read_b128 v[26:29], v84 offset:31168
	ds_read_b128 v[38:41], v84 offset:31936
	v_pk_fma_f32 v[2:3], v[148:149], v[12:13], v[6:7] op_sel_hi:[1,0,1] neg_lo:[0,1,0] neg_hi:[0,1,0]
	v_pk_fma_f32 v[4:5], v[150:151], v[12:13], v[8:9] op_sel_hi:[1,0,1] neg_lo:[0,1,0] neg_hi:[0,1,0]
	s_waitcnt lgkmcnt(5)
	v_pk_mul_f32 v[10:11], v[2:3], v[180:181]
	v_pk_fma_f32 v[10:11], v[4:5], v[182:183], v[10:11]
	v_pk_mul_f32 v[14:15], v[2:3], v[160:161]
	v_add_f32_e32 v12, v10, v11
	v_pk_fma_f32 v[14:15], v[4:5], v[162:163], v[14:15]
	v_add_f32_e32 v113, v14, v15
	v_add_f32_dpp v12, v12, v12 quad_perm:[1,0,3,2] row_mask:0xf bank_mask:0xf bound_ctrl:1
	v_pk_mul_f32 v[6:7], v[176:177], v[94:95] op_sel_hi:[1,0]
	v_pk_mul_f32 v[8:9], v[178:179], v[94:95] op_sel_hi:[1,0]
	v_add_f32_dpp v12, v12, v12 quad_perm:[2,3,0,1] row_mask:0xf bank_mask:0xf bound_ctrl:1
	v_pk_fma_f32 v[6:7], v[2:3], v[168:169], v[6:7]
	v_pk_fma_f32 v[8:9], v[4:5], v[170:171], v[8:9]
	v_add_f32_dpp v12, v12, v12 row_half_mirror row_mask:0xf bank_mask:0xf bound_ctrl:1
	ds_read_b128 v[132:135], v84 offset:33024
	ds_read_b128 v[120:123], v84 offset:32256
	v_add_f32_dpp v12, v12, v12 row_mirror row_mask:0xf bank_mask:0xf bound_ctrl:1
	ds_read_b128 v[128:131], v84 offset:32768
	ds_read_b128 v[116:119], v96 offset:96
	ds_read_b128 v[124:127], v84 offset:32512
	ds_read_b128 v[136:139], v84 offset:33280
	v_pk_fma_f32 v[2:3], v[172:173], v[12:13], v[6:7] op_sel_hi:[1,0,1] neg_lo:[0,1,0] neg_hi:[0,1,0]
	v_pk_fma_f32 v[4:5], v[174:175], v[12:13], v[8:9] op_sel_hi:[1,0,1] neg_lo:[0,1,0] neg_hi:[0,1,0]
	s_waitcnt lgkmcnt(6)
; #define LAS __attribute__((address_space(3)))
; template <int CTRL> __device__ __forceinline__ float dpp_f(float v) { return __int_as_float(__builtin_amdgcn_update_dpp(0, __float_as_int(v), CTRL, 0xf, 0xf, true)); }
; __device__ __forceinline__ float row16_sum(float v) { v += dpp_f<0xB1>(v); v += dpp_f<0x4E>(v); v += dpp_f<0x141>(v); v += dpp_f<0x140>(v); return v; }
; __device__ __forceinline__ float tr16_sum(const float (&p)[16], int kq) {
;     const bool b3 = (kq & 8) != 0, b2 = (kq & 4) != 0, b1 = (kq & 2) != 0, b0 = (kq & 1) != 0;
;     float q[8], r[4], u[2];
; #pragma unroll
;     for (int t = 0; t < 8; ++t) { const float keep = b3 ? p[t + 8] : p[t], send = b3 ? p[t] : p[t + 8]; q[t] = keep + dpp_f<0x140>(send); }
; #pragma unroll
;     for (int t = 0; t < 4; ++t) { const float keep = b2 ? q[t + 4] : q[t], send = b2 ? q[t] : q[t + 4]; r[t] = keep + dpp_f<0x141>(send); }
; #pragma unroll
;     for (int t = 0; t < 2; ++t) { const float keep = b1 ? r[t + 2] : r[t], send = b1 ? r[t] : r[t + 2]; u[t] = keep + dpp_f<0x4E>(send); }
;     const float keep = b0 ? u[1] : u[0], send = b0 ? u[0] : u[1];
;     return keep + dpp_f<0xB1>(send);
; __device__ __forceinline__ void rwkv_scan_unit(LAS unsigned char* lds, const float* Wd, const float* V, const bf16_t* RKKB, float* Yraw, int p, int rg, int tid) {
;     ...
;             for (int st = 0; st < SCAN_CH; ++st) {
;                 f32x4 wn = w, bn = b, kn = k, kkn = kk, rn = r; float vn = v;
;                 if (st + 1 < SCAN_CH) { const int o = (st + 1) * SCAN_STEP_B;
;                     wn = *(LAS const f32x4*)(sl + o); bn = *(LAS const f32x4*)(sl + o + 256); kn = *(LAS const f32x4*)(sl + o + 512); kkn = *(LAS const f32x4*)(sl + o + 768); rn = *(LAS const f32x4*)(sl + o + 1024);
;                     vn = *(LAS const float*)(vl + o); }
;                 float sa = (S[0] * kk[0] + S[1] * kk[1]) + (S[2] * kk[2] + S[3] * kk[3]);
;                 const f32x4 kvt = k * v;
;                 sa = -row16_sum(sa);
;                 S = S * w + (b * sa + kvt);
;                 yp[st & 15] = (S[0] * r[0] + S[1] * r[1]) + (S[2] * r[2] + S[3] * r[3]);
;                 if ((st & 15) == 15) yo[(size_t)(st - 15) * 64] = tr16_sum(yp, kq);
	v_pk_mul_f32 v[10:11], v[2:3], v[34:35]
	v_pk_fma_f32 v[10:11], v[4:5], v[36:37], v[10:11]
	v_pk_mul_f32 v[14:15], v[2:3], v[184:185]
	v_add_f32_e32 v12, v10, v11
	v_pk_fma_f32 v[14:15], v[4:5], v[186:187], v[14:15]
	v_add_f32_e32 v114, v14, v15
	v_add_f32_dpp v12, v12, v12 quad_perm:[1,0,3,2] row_mask:0xf bank_mask:0xf bound_ctrl:1
	v_pk_mul_f32 v[6:7], v[30:31], v[94:95] op_sel:[0,1] op_sel_hi:[1,1]
	v_pk_mul_f32 v[8:9], v[32:33], v[94:95] op_sel:[0,1] op_sel_hi:[1,1]
	v_add_f32_dpp v12, v12, v12 quad_perm:[2,3,0,1] row_mask:0xf bank_mask:0xf bound_ctrl:1
	v_pk_fma_f32 v[6:7], v[2:3], v[22:23], v[6:7]
	v_pk_fma_f32 v[8:9], v[4:5], v[24:25], v[8:9]
	v_add_f32_dpp v12, v12, v12 row_half_mirror row_mask:0xf bank_mask:0xf bound_ctrl:1
	ds_read_b128 v[156:159], v84 offset:34368
	ds_read_b128 v[144:147], v84 offset:33600
	v_add_f32_dpp v12, v12, v12 row_mirror row_mask:0xf bank_mask:0xf bound_ctrl:1
	ds_read_b128 v[152:155], v84 offset:34112
	ds_read_b128 v[148:151], v84 offset:33856
	ds_read_b128 v[160:163], v84 offset:34624
	v_pk_fma_f32 v[2:3], v[26:27], v[12:13], v[6:7] op_sel_hi:[1,0,1] neg_lo:[0,1,0] neg_hi:[0,1,0]
	v_pk_fma_f32 v[4:5], v[28:29], v[12:13], v[8:9] op_sel_hi:[1,0,1] neg_lo:[0,1,0] neg_hi:[0,1,0]
	s_waitcnt lgkmcnt(5)
	v_pk_mul_f32 v[10:11], v[2:3], v[132:133]
	v_pk_fma_f32 v[10:11], v[4:5], v[134:135], v[10:11]
	v_pk_mul_f32 v[14:15], v[2:3], v[38:39]
	v_add_f32_e32 v12, v10, v11
	v_pk_fma_f32 v[14:15], v[4:5], v[40:41], v[14:15]
	v_add_f32_e32 v115, v14, v15
	v_add_f32_dpp v12, v12, v12 quad_perm:[1,0,3,2] row_mask:0xf bank_mask:0xf bound_ctrl:1
	v_pk_mul_f32 v[6:7], v[128:129], v[116:117] op_sel_hi:[1,0]
	v_pk_mul_f32 v[8:9], v[130:131], v[116:117] op_sel_hi:[1,0]
	v_add_f32_dpp v12, v12, v12 quad_perm:[2,3,0,1] row_mask:0xf bank_mask:0xf bound_ctrl:1
	v_pk_fma_f32 v[6:7], v[2:3], v[120:121], v[6:7]
	v_pk_fma_f32 v[8:9], v[4:5], v[122:123], v[8:9]
	v_add_f32_dpp v12, v12, v12 row_half_mirror row_mask:0xf bank_mask:0xf bound_ctrl:1
	ds_read_b128 v[180:183], v84 offset:35712
	ds_read_b128 v[168:171], v84 offset:34944
	v_add_f32_dpp v12, v12, v12 row_mirror row_mask:0xf bank_mask:0xf bound_ctrl:1
	ds_read_b128 v[176:179], v84 offset:35456
	ds_read_b128 v[172:175], v84 offset:35200
	ds_read_b128 v[184:187], v84 offset:35968
	v_pk_fma_f32 v[2:3], v[124:125], v[12:13], v[6:7] op_sel_hi:[1,0,1] neg_lo:[0,1,0] neg_hi:[0,1,0]
	v_pk_fma_f32 v[4:5], v[126:127], v[12:13], v[8:9] op_sel_hi:[1,0,1] neg_lo:[0,1,0] neg_hi:[0,1,0]
	s_waitcnt lgkmcnt(5)
	v_pk_mul_f32 v[10:11], v[2:3], v[156:157]
	v_pk_fma_f32 v[10:11], v[4:5], v[158:159], v[10:11]
	v_pk_mul_f32 v[14:15], v[2:3], v[136:137]
	v_add_f32_e32 v12, v10, v11
	v_pk_fma_f32 v[14:15], v[4:5], v[138:139], v[14:15]
	v_add_f32_e32 v44, v14, v15
	v_add_f32_dpp v12, v12, v12 quad_perm:[1,0,3,2] row_mask:0xf bank_mask:0xf bound_ctrl:1
	v_add_f32_dpp v108, v108, v108 row_mirror row_mask:0xf bank_mask:0x3 bound_ctrl:1
	v_add_f32_dpp v108, v44, v44 row_mirror row_mask:0xf bank_mask:0xc bound_ctrl:1
	v_add_f32_dpp v12, v12, v12 quad_perm:[2,3,0,1] row_mask:0xf bank_mask:0xf bound_ctrl:1
	v_pk_mul_f32 v[6:7], v[152:153], v[116:117] op_sel:[0,1] op_sel_hi:[1,1]
	v_pk_mul_f32 v[8:9], v[154:155], v[116:117] op_sel:[0,1] op_sel_hi:[1,1]
	v_add_f32_dpp v12, v12, v12 row_half_mirror row_mask:0xf bank_mask:0xf bound_ctrl:1
	v_pk_fma_f32 v[6:7], v[2:3], v[144:145], v[6:7]
	v_pk_fma_f32 v[8:9], v[4:5], v[146:147], v[8:9]
	v_add_f32_dpp v12, v12, v12 row_mirror row_mask:0xf bank_mask:0xf bound_ctrl:1
	ds_read_b128 v[34:37], v84 offset:37056
	ds_read_b128 v[22:25], v84 offset:36288
	ds_read_b128 v[30:33], v84 offset:36800
	ds_read_b128 v[26:29], v84 offset:36544
	ds_read_b128 v[38:41], v84 offset:37312
	v_pk_fma_f32 v[2:3], v[148:149], v[12:13], v[6:7] op_sel_hi:[1,0,1] neg_lo:[0,1,0] neg_hi:[0,1,0]
	v_pk_fma_f32 v[4:5], v[150:151], v[12:13], v[8:9] op_sel_hi:[1,0,1] neg_lo:[0,1,0] neg_hi:[0,1,0]
	s_waitcnt lgkmcnt(5)
	v_pk_mul_f32 v[10:11], v[2:3], v[180:181]
	v_pk_fma_f32 v[10:11], v[4:5], v[182:183], v[10:11]
	v_pk_mul_f32 v[14:15], v[2:3], v[160:161]
	v_add_f32_e32 v12, v10, v11
	v_pk_fma_f32 v[14:15], v[4:5], v[162:163], v[14:15]
	v_add_f32_e32 v44, v14, v15
	v_add_f32_dpp v12, v12, v12 quad_perm:[1,0,3,2] row_mask:0xf bank_mask:0xf bound_ctrl:1
	v_add_f32_dpp v109, v109, v109 row_mirror row_mask:0xf bank_mask:0x3 bound_ctrl:1
	v_add_f32_dpp v109, v44, v44 row_mirror row_mask:0xf bank_mask:0xc bound_ctrl:1
	v_add_f32_dpp v12, v12, v12 quad_perm:[2,3,0,1] row_mask:0xf bank_mask:0xf bound_ctrl:1
	v_pk_mul_f32 v[6:7], v[176:177], v[118:119] op_sel_hi:[1,0]
	v_pk_mul_f32 v[8:9], v[178:179], v[118:119] op_sel_hi:[1,0]
	v_add_f32_dpp v12, v12, v12 row_half_mirror row_mask:0xf bank_mask:0xf bound_ctrl:1
	v_pk_fma_f32 v[6:7], v[2:3], v[168:169], v[6:7]
	v_pk_fma_f32 v[8:9], v[4:5], v[170:171], v[8:9]
	v_add_f32_dpp v12, v12, v12 row_mirror row_mask:0xf bank_mask:0xf bound_ctrl:1
	ds_read_b128 v[132:135], v84 offset:38400
	ds_read_b128 v[120:123], v84 offset:37632
	ds_read_b128 v[128:131], v84 offset:38144
	ds_read_b128 v[92:95], v96 offset:112
	ds_read_b128 v[124:127], v84 offset:37888
	ds_read_b128 v[136:139], v84 offset:38656
	v_pk_fma_f32 v[2:3], v[172:173], v[12:13], v[6:7] op_sel_hi:[1,0,1] neg_lo:[0,1,0] neg_hi:[0,1,0]
	v_pk_fma_f32 v[4:5], v[174:175], v[12:13], v[8:9] op_sel_hi:[1,0,1] neg_lo:[0,1,0] neg_hi:[0,1,0]
	s_waitcnt lgkmcnt(6)
; #define LAS __attribute__((address_space(3)))
; template <int CTRL> __device__ __forceinline__ float dpp_f(float v) { return __int_as_float(__builtin_amdgcn_update_dpp(0, __float_as_int(v), CTRL, 0xf, 0xf, true)); }
; __device__ __forceinline__ float row16_sum(float v) { v += dpp_f<0xB1>(v); v += dpp_f<0x4E>(v); v += dpp_f<0x141>(v); v += dpp_f<0x140>(v); return v; }
; __device__ __forceinline__ float tr16_sum(const float (&p)[16], int kq) {
;     const bool b3 = (kq & 8) != 0, b2 = (kq & 4) != 0, b1 = (kq & 2) != 0, b0 = (kq & 1) != 0;
;     float q[8], r[4], u[2];
; #pragma unroll
;     for (int t = 0; t < 8; ++t) { const float keep = b3 ? p[t + 8] : p[t], send = b3 ? p[t] : p[t + 8]; q[t] = keep + dpp_f<0x140>(send); }
; #pragma unroll
;     for (int t = 0; t < 4; ++t) { const float keep = b2 ? q[t + 4] : q[t], send = b2 ? q[t] : q[t + 4]; r[t] = keep + dpp_f<0x141>(send); }
; #pragma unroll
;     for (int t = 0; t < 2; ++t) { const float keep = b1 ? r[t + 2] : r[t], send = b1 ? r[t] : r[t + 2]; u[t] = keep + dpp_f<0x4E>(send); }
;     const float keep = b0 ? u[1] : u[0], send = b0 ? u[0] : u[1];
;     return keep + dpp_f<0xB1>(send);
; __device__ __forceinline__ void rwkv_scan_unit(LAS unsigned char* lds, const float* Wd, const float* V, const bf16_t* RKKB, float* Yraw, int p, int rg, int tid) {
;     ...
;             for (int st = 0; st < SCAN_CH; ++st) {
;                 f32x4 wn = w, bn = b, kn = k, kkn = kk, rn = r; float vn = v;
;                 if (st + 1 < SCAN_CH) { const int o = (st + 1) * SCAN_STEP_B;
;                     wn = *(LAS const f32x4*)(sl + o); bn = *(LAS const f32x4*)(sl + o + 256); kn = *(LAS const f32x4*)(sl + o + 512); kkn = *(LAS const f32x4*)(sl + o + 768); rn = *(LAS const f32x4*)(sl + o + 1024);
;                     vn = *(LAS const float*)(vl + o); }
;                 float sa = (S[0] * kk[0] + S[1] * kk[1]) + (S[2] * kk[2] + S[3] * kk[3]);
;                 const f32x4 kvt = k * v;
;                 sa = -row16_sum(sa);
;                 S = S * w + (b * sa + kvt);
;                 yp[st & 15] = (S[0] * r[0] + S[1] * r[1]) + (S[2] * r[2] + S[3] * r[3]);
;                 if ((st & 15) == 15) yo[(size_t)(st - 15) * 64] = tr16_sum(yp, kq);
	v_pk_mul_f32 v[10:11], v[2:3], v[34:35]
	v_pk_fma_f32 v[10:11], v[4:5], v[36:37], v[10:11]
	v_pk_mul_f32 v[14:15], v[2:3], v[184:185]
	v_add_f32_e32 v12, v10, v11
	v_pk_fma_f32 v[14:15], v[4:5], v[186:187], v[14:15]
	v_add_f32_e32 v44, v14, v15
	v_add_f32_dpp v12, v12, v12 quad_perm:[1,0,3,2] row_mask:0xf bank_mask:0xf bound_ctrl:1
	v_add_f32_dpp v110, v110, v110 row_mirror row_mask:0xf bank_mask:0x3 bound_ctrl:1
	v_add_f32_dpp v110, v44, v44 row_mirror row_mask:0xf bank_mask:0xc bound_ctrl:1
	v_add_f32_dpp v12, v12, v12 quad_perm:[2,3,0,1] row_mask:0xf bank_mask:0xf bound_ctrl:1
	v_pk_mul_f32 v[6:7], v[30:31], v[118:119] op_sel:[0,1] op_sel_hi:[1,1]
	v_pk_mul_f32 v[8:9], v[32:33], v[118:119] op_sel:[0,1] op_sel_hi:[1,1]
	v_add_f32_dpp v12, v12, v12 row_half_mirror row_mask:0xf bank_mask:0xf bound_ctrl:1
	v_pk_fma_f32 v[6:7], v[2:3], v[22:23], v[6:7]
	v_pk_fma_f32 v[8:9], v[4:5], v[24:25], v[8:9]
	v_add_f32_dpp v12, v12, v12 row_mirror row_mask:0xf bank_mask:0xf bound_ctrl:1
	ds_read_b128 v[156:159], v84 offset:39744
	ds_read_b128 v[144:147], v84 offset:38976
	ds_read_b128 v[152:155], v84 offset:39488
	ds_read_b128 v[148:151], v84 offset:39232
	ds_read_b128 v[160:163], v84 offset:40000
	v_pk_fma_f32 v[2:3], v[26:27], v[12:13], v[6:7] op_sel_hi:[1,0,1] neg_lo:[0,1,0] neg_hi:[0,1,0]
	v_pk_fma_f32 v[4:5], v[28:29], v[12:13], v[8:9] op_sel_hi:[1,0,1] neg_lo:[0,1,0] neg_hi:[0,1,0]
	s_waitcnt lgkmcnt(5)
	v_pk_mul_f32 v[10:11], v[2:3], v[132:133]
	v_pk_fma_f32 v[10:11], v[4:5], v[134:135], v[10:11]
	v_pk_mul_f32 v[14:15], v[2:3], v[38:39]
	v_add_f32_e32 v12, v10, v11
	v_pk_fma_f32 v[14:15], v[4:5], v[40:41], v[14:15]
	v_add_f32_e32 v44, v14, v15
	v_add_f32_dpp v12, v12, v12 quad_perm:[1,0,3,2] row_mask:0xf bank_mask:0xf bound_ctrl:1
	v_add_f32_dpp v111, v111, v111 row_mirror row_mask:0xf bank_mask:0x3 bound_ctrl:1
	v_add_f32_dpp v111, v44, v44 row_mirror row_mask:0xf bank_mask:0xc bound_ctrl:1
	v_add_f32_dpp v12, v12, v12 quad_perm:[2,3,0,1] row_mask:0xf bank_mask:0xf bound_ctrl:1
	v_pk_mul_f32 v[6:7], v[128:129], v[92:93] op_sel_hi:[1,0]
	v_pk_mul_f32 v[8:9], v[130:131], v[92:93] op_sel_hi:[1,0]
	v_add_f32_dpp v12, v12, v12 row_half_mirror row_mask:0xf bank_mask:0xf bound_ctrl:1
	v_pk_fma_f32 v[6:7], v[2:3], v[120:121], v[6:7]
	v_pk_fma_f32 v[8:9], v[4:5], v[122:123], v[8:9]
	v_add_f32_dpp v12, v12, v12 row_mirror row_mask:0xf bank_mask:0xf bound_ctrl:1
	ds_read_b128 v[180:183], v84 offset:41088
	ds_read_b128 v[168:171], v84 offset:40320
	ds_read_b128 v[176:179], v84 offset:40832
	ds_read_b128 v[172:175], v84 offset:40576
	ds_read_b128 v[184:187], v84 offset:41344
	v_pk_fma_f32 v[2:3], v[124:125], v[12:13], v[6:7] op_sel_hi:[1,0,1] neg_lo:[0,1,0] neg_hi:[0,1,0]
	v_pk_fma_f32 v[4:5], v[126:127], v[12:13], v[8:9] op_sel_hi:[1,0,1] neg_lo:[0,1,0] neg_hi:[0,1,0]
	s_waitcnt lgkmcnt(5)
	v_pk_mul_f32 v[10:11], v[2:3], v[156:157]
	v_pk_fma_f32 v[10:11], v[4:5], v[158:159], v[10:11]
	v_pk_mul_f32 v[14:15], v[2:3], v[136:137]
	v_add_f32_e32 v12, v10, v11
	v_pk_fma_f32 v[14:15], v[4:5], v[138:139], v[14:15]
	v_add_f32_e32 v44, v14, v15
	v_add_f32_dpp v12, v12, v12 quad_perm:[1,0,3,2] row_mask:0xf bank_mask:0xf bound_ctrl:1
	v_add_f32_dpp v112, v112, v112 row_mirror row_mask:0xf bank_mask:0x3 bound_ctrl:1
	v_add_f32_dpp v112, v44, v44 row_mirror row_mask:0xf bank_mask:0xc bound_ctrl:1
	v_add_f32_dpp v12, v12, v12 quad_perm:[2,3,0,1] row_mask:0xf bank_mask:0xf bound_ctrl:1
	v_pk_mul_f32 v[6:7], v[152:153], v[92:93] op_sel:[0,1] op_sel_hi:[1,1]
	v_pk_mul_f32 v[8:9], v[154:155], v[92:93] op_sel:[0,1] op_sel_hi:[1,1]
	v_add_f32_dpp v12, v12, v12 row_half_mirror row_mask:0xf bank_mask:0xf bound_ctrl:1
	v_pk_fma_f32 v[6:7], v[2:3], v[144:145], v[6:7]
	v_pk_fma_f32 v[8:9], v[4:5], v[146:147], v[8:9]
	v_add_f32_dpp v12, v12, v12 row_mirror row_mask:0xf bank_mask:0xf bound_ctrl:1
	ds_read_b128 v[34:37], v84 offset:42432
	ds_read_b128 v[22:25], v84 offset:41664
	ds_read_b128 v[30:33], v84 offset:42176
	ds_read_b128 v[26:29], v84 offset:41920
	ds_read_b128 v[38:41], v84 offset:42688
	v_pk_fma_f32 v[2:3], v[148:149], v[12:13], v[6:7] op_sel_hi:[1,0,1] neg_lo:[0,1,0] neg_hi:[0,1,0]
	v_pk_fma_f32 v[4:5], v[150:151], v[12:13], v[8:9] op_sel_hi:[1,0,1] neg_lo:[0,1,0] neg_hi:[0,1,0]
	s_waitcnt lgkmcnt(5)
; #define LAS __attribute__((address_space(3)))
; template <int CTRL> __device__ __forceinline__ float dpp_f(float v) { return __int_as_float(__builtin_amdgcn_update_dpp(0, __float_as_int(v), CTRL, 0xf, 0xf, true)); }
; __device__ __forceinline__ float row16_sum(float v) { v += dpp_f<0xB1>(v); v += dpp_f<0x4E>(v); v += dpp_f<0x141>(v); v += dpp_f<0x140>(v); return v; }
; __device__ __forceinline__ float tr16_sum(const float (&p)[16], int kq) {
;     const bool b3 = (kq & 8) != 0, b2 = (kq & 4) != 0, b1 = (kq & 2) != 0, b0 = (kq & 1) != 0;
;     float q[8], r[4], u[2];
; #pragma unroll
;     for (int t = 0; t < 8; ++t) { const float keep = b3 ? p[t + 8] : p[t], send = b3 ? p[t] : p[t + 8]; q[t] = keep + dpp_f<0x140>(send); }
; #pragma unroll
;     for (int t = 0; t < 4; ++t) { const float keep = b2 ? q[t + 4] : q[t], send = b2 ? q[t] : q[t + 4]; r[t] = keep + dpp_f<0x141>(send); }
; #pragma unroll
;     for (int t = 0; t < 2; ++t) { const float keep = b1 ? r[t + 2] : r[t], send = b1 ? r[t] : r[t + 2]; u[t] = keep + dpp_f<0x4E>(send); }
;     const float keep = b0 ? u[1] : u[0], send = b0 ? u[0] : u[1];
;     return keep + dpp_f<0xB1>(send);
; __device__ __forceinline__ void rwkv_scan_unit(LAS unsigned char* lds, const float* Wd, const float* V, const bf16_t* RKKB, float* Yraw, int p, int rg, int tid) {
;     ...
;             for (int st = 0; st < SCAN_CH; ++st) {
;                 f32x4 wn = w, bn = b, kn = k, kkn = kk, rn = r; float vn = v;
;                 if (st + 1 < SCAN_CH) { const int o = (st + 1) * SCAN_STEP_B;
;                     wn = *(LAS const f32x4*)(sl + o); bn = *(LAS const f32x4*)(sl + o + 256); kn = *(LAS const f32x4*)(sl + o + 512); kkn = *(LAS const f32x4*)(sl + o + 768); rn = *(LAS const f32x4*)(sl + o + 1024);
;                     vn = *(LAS const float*)(vl + o); }
;                 float sa = (S[0] * kk[0] + S[1] * kk[1]) + (S[2] * kk[2] + S[3] * kk[3]);
;                 const f32x4 kvt = k * v;
;                 sa = -row16_sum(sa);
;                 S = S * w + (b * sa + kvt);
;                 yp[st & 15] = (S[0] * r[0] + S[1] * r[1]) + (S[2] * r[2] + S[3] * r[3]);
;                 if ((st & 15) == 15) yo[(size_t)(st - 15) * 64] = tr16_sum(yp, kq);
;                 w = wn; b = bn; k = kn; kk = kkn; r = rn; v = vn;
;             }
;         }
;         __syncthreads();
;     }
	v_pk_mul_f32 v[10:11], v[2:3], v[180:181]
	v_pk_fma_f32 v[10:11], v[4:5], v[182:183], v[10:11]
	v_pk_mul_f32 v[14:15], v[2:3], v[160:161]
	v_add_f32_e32 v12, v10, v11
	v_pk_fma_f32 v[14:15], v[4:5], v[162:163], v[14:15]
	v_add_f32_e32 v44, v14, v15
	v_add_f32_dpp v12, v12, v12 quad_perm:[1,0,3,2] row_mask:0xf bank_mask:0xf bound_ctrl:1
	v_add_f32_dpp v113, v113, v113 row_mirror row_mask:0xf bank_mask:0x3 bound_ctrl:1
	v_add_f32_dpp v113, v44, v44 row_mirror row_mask:0xf bank_mask:0xc bound_ctrl:1
	v_add_f32_dpp v12, v12, v12 quad_perm:[2,3,0,1] row_mask:0xf bank_mask:0xf bound_ctrl:1
	v_pk_mul_f32 v[6:7], v[176:177], v[94:95] op_sel_hi:[1,0]
	v_pk_mul_f32 v[8:9], v[178:179], v[94:95] op_sel_hi:[1,0]
	v_add_f32_dpp v12, v12, v12 row_half_mirror row_mask:0xf bank_mask:0xf bound_ctrl:1
	v_pk_fma_f32 v[6:7], v[2:3], v[168:169], v[6:7]
	v_pk_fma_f32 v[8:9], v[4:5], v[170:171], v[8:9]
	v_add_f32_dpp v12, v12, v12 row_mirror row_mask:0xf bank_mask:0xf bound_ctrl:1
	ds_read_b128 v[132:135], v86 offset:768
	ds_read_b128 v[120:123], v86
	ds_read_b128 v[128:131], v86 offset:512
	ds_read_b128 v[116:119], v97
	ds_read_b128 v[124:127], v86 offset:256
	ds_read_b128 v[136:139], v86 offset:1024
	v_pk_fma_f32 v[2:3], v[172:173], v[12:13], v[6:7] op_sel_hi:[1,0,1] neg_lo:[0,1,0] neg_hi:[0,1,0]
	v_pk_fma_f32 v[4:5], v[174:175], v[12:13], v[8:9] op_sel_hi:[1,0,1] neg_lo:[0,1,0] neg_hi:[0,1,0]
	s_waitcnt lgkmcnt(6)
	v_pk_mul_f32 v[10:11], v[2:3], v[34:35]
	v_pk_fma_f32 v[10:11], v[4:5], v[36:37], v[10:11]
	v_pk_mul_f32 v[14:15], v[2:3], v[184:185]
	v_add_f32_e32 v12, v10, v11
	v_pk_fma_f32 v[14:15], v[4:5], v[186:187], v[14:15]
	v_add_f32_e32 v44, v14, v15
	v_add_f32_dpp v12, v12, v12 quad_perm:[1,0,3,2] row_mask:0xf bank_mask:0xf bound_ctrl:1
	v_add_f32_dpp v114, v114, v114 row_mirror row_mask:0xf bank_mask:0x3 bound_ctrl:1
	v_add_f32_dpp v114, v44, v44 row_mirror row_mask:0xf bank_mask:0xc bound_ctrl:1
	v_add_f32_dpp v12, v12, v12 quad_perm:[2,3,0,1] row_mask:0xf bank_mask:0xf bound_ctrl:1
	v_pk_mul_f32 v[6:7], v[30:31], v[94:95] op_sel:[0,1] op_sel_hi:[1,1]
	v_pk_mul_f32 v[8:9], v[32:33], v[94:95] op_sel:[0,1] op_sel_hi:[1,1]
	v_add_f32_dpp v12, v12, v12 row_half_mirror row_mask:0xf bank_mask:0xf bound_ctrl:1
	v_pk_fma_f32 v[6:7], v[2:3], v[22:23], v[6:7]
	v_pk_fma_f32 v[8:9], v[4:5], v[24:25], v[8:9]
	v_add_f32_dpp v12, v12, v12 row_mirror row_mask:0xf bank_mask:0xf bound_ctrl:1
	ds_read_b128 v[156:159], v86 offset:2112
	ds_read_b128 v[144:147], v86 offset:1344
	ds_read_b128 v[152:155], v86 offset:1856
	ds_read_b128 v[148:151], v86 offset:1600
	ds_read_b128 v[160:163], v86 offset:2368
	v_pk_fma_f32 v[2:3], v[26:27], v[12:13], v[6:7] op_sel_hi:[1,0,1] neg_lo:[0,1,0] neg_hi:[0,1,0]
	v_pk_fma_f32 v[4:5], v[28:29], v[12:13], v[8:9] op_sel_hi:[1,0,1] neg_lo:[0,1,0] neg_hi:[0,1,0]
	v_pk_mul_f32 v[14:15], v[2:3], v[38:39]
	v_pk_fma_f32 v[14:15], v[4:5], v[40:41], v[14:15]
	v_add_f32_e32 v44, v14, v15
	v_add_f32_dpp v115, v115, v115 row_mirror row_mask:0xf bank_mask:0x3 bound_ctrl:1
	s_nop 0
	v_add_f32_dpp v115, v44, v44 row_mirror row_mask:0xf bank_mask:0xc bound_ctrl:1
	v_add_f32_dpp v108, v108, v108 row_half_mirror row_mask:0xf bank_mask:0x5 bound_ctrl:1
	v_add_f32_dpp v108, v112, v112 row_half_mirror row_mask:0xf bank_mask:0xa bound_ctrl:1
	v_add_f32_dpp v109, v109, v109 row_half_mirror row_mask:0xf bank_mask:0x5 bound_ctrl:1
	v_add_f32_dpp v109, v113, v113 row_half_mirror row_mask:0xf bank_mask:0xa bound_ctrl:1
	v_add_f32_dpp v110, v110, v110 row_half_mirror row_mask:0xf bank_mask:0x5 bound_ctrl:1
	v_add_f32_dpp v110, v114, v114 row_half_mirror row_mask:0xf bank_mask:0xa bound_ctrl:1
	v_add_f32_dpp v111, v111, v111 row_half_mirror row_mask:0xf bank_mask:0x5 bound_ctrl:1
	v_add_f32_dpp v111, v115, v115 row_half_mirror row_mask:0xf bank_mask:0xa bound_ctrl:1
	v_cndmask_b32_e64 v16, v110, v108, s[8:9]
	v_cndmask_b32_e64 v17, v108, v110, s[8:9]
	s_nop 1
	v_add_f32_dpp v16, v17, v16 quad_perm:[2,3,0,1] row_mask:0xf bank_mask:0xf bound_ctrl:1
	v_cndmask_b32_e64 v18, v111, v109, s[8:9]
	v_cndmask_b32_e64 v19, v109, v111, s[8:9]
	s_nop 1
	v_add_f32_dpp v18, v19, v18 quad_perm:[2,3,0,1] row_mask:0xf bank_mask:0xf bound_ctrl:1
	v_cndmask_b32_e64 v17, v18, v16, s[10:11]
	v_cndmask_b32_e64 v19, v16, v18, s[10:11]
	s_nop 1
	v_add_f32_dpp v17, v19, v17 quad_perm:[1,0,3,2] row_mask:0xf bank_mask:0xf bound_ctrl:1
	global_store_dword v[90:91], v17, off
	s_add_i32 s22, s22, 1
	s_mov_b32 s18, s19
	s_add_i32 s19, s19, 0xa800
	s_cmp_eq_u32 s19, 0x1f800
	s_cselect_b32 s19, 0, s19
	s_cmpk_eq_i32 s22, 0x80
	s_barrier
	s_cbranch_scc1 .LBB0_370
	s_branch .Lscan_top
